# solve: one lgkmcnt wait per pair of L pieces
# speedup vs baseline: 1.0404x; 1.0014x over previous
; #define LAS __attribute__((address_space(3)))
; __device__ __forceinline__ void even_prep(const Ctx& c, const Params& p, int e) {
;     ...
;         if (tid_i < 256) { const int cc = tid_i & 127; const LAS float* src = (tid_i < 128) ? VB : KBG; float x[64];
;             int vz = 0; asm volatile("" : "+v"(vz)); const LAS float* Lv = Lm + vz;
; #pragma unroll
;             for (int i = 0; i < 64; ++i) x[i] = src[i * 128 + cc];
; #pragma unroll
;             for (int i = 1; i < 64; ++i) { const LAS f32x4* Lr = (const LAS f32x4*)(Lv + i * 64); float a0 = x[i], a1 = 0.f;
; #pragma unroll
;                 for (int j4 = 0; j4 < (i + 3) / 4; ++j4) { const f32x4 l = Lr[j4];
;                     if (4 * j4 + 0 < i) a0 -= l[0] * x[4 * j4 + 0];
;                     if (4 * j4 + 1 < i) a1 -= l[1] * x[4 * j4 + 1];
;                     if (4 * j4 + 2 < i) a0 -= l[2] * x[4 * j4 + 2];
;                     if (4 * j4 + 3 < i) a1 -= l[3] * x[4 * j4 + 3]; }
;                 x[i] = a0 + a1; }
.LBB0_788:
	s_movk_i32 s0, 0x100
	v_cmp_gt_i32_e32 vcc, s0, v18
	s_waitcnt lgkmcnt(0)
	s_barrier
	s_and_saveexec_b64 s[6:7], vcc
	s_cbranch_execz .LBB0_790
	v_mov_b32_e32 v1, s42
	v_mov_b32_e32 v2, s39
	v_and_b32_e32 v16, 0x7f, v18
	v_cndmask_b32_e64 v1, v1, v2, s[4:5]
	v_mov_b32_e32 v17, s48
	v_lshl_add_u32 v16, v16, 2, v1
	ds_read2st64_b32 v[92:93], v16 offset0:0 offset1:2
	ds_read2st64_b32 v[94:95], v16 offset0:4 offset1:6
	ds_read2st64_b32 v[96:97], v16 offset0:8 offset1:10
	ds_read2st64_b32 v[98:99], v16 offset0:12 offset1:14
	ds_read2st64_b32 v[100:101], v16 offset0:16 offset1:18
	ds_read2st64_b32 v[102:103], v16 offset0:20 offset1:22
	ds_read2st64_b32 v[104:105], v16 offset0:24 offset1:26
	ds_read2st64_b32 v[106:107], v16 offset0:28 offset1:30
	ds_read2st64_b32 v[108:109], v16 offset0:32 offset1:34
	ds_read2st64_b32 v[110:111], v16 offset0:36 offset1:38
	ds_read2st64_b32 v[112:113], v16 offset0:40 offset1:42
	ds_read2st64_b32 v[114:115], v16 offset0:44 offset1:46
	ds_read2st64_b32 v[116:117], v16 offset0:48 offset1:50
	ds_read2st64_b32 v[118:119], v16 offset0:52 offset1:54
	ds_read2st64_b32 v[120:121], v16 offset0:56 offset1:58
	s_waitcnt lgkmcnt(7)
	ds_read2st64_b32 v[122:123], v16 offset0:60 offset1:62
	ds_read2st64_b32 v[124:125], v16 offset0:64 offset1:66
	ds_read2st64_b32 v[126:127], v16 offset0:68 offset1:70
	ds_read2st64_b32 v[128:129], v16 offset0:72 offset1:74
	ds_read2st64_b32 v[130:131], v16 offset0:76 offset1:78
	ds_read2st64_b32 v[132:133], v16 offset0:80 offset1:82
	ds_read2st64_b32 v[134:135], v16 offset0:84 offset1:86
	ds_read2st64_b32 v[136:137], v16 offset0:88 offset1:90
	s_waitcnt lgkmcnt(7)
	ds_read2st64_b32 v[138:139], v16 offset0:92 offset1:94
	ds_read2st64_b32 v[140:141], v16 offset0:96 offset1:98
	ds_read2st64_b32 v[142:143], v16 offset0:100 offset1:102
	ds_read2st64_b32 v[60:61], v16 offset0:104 offset1:106
	ds_read2st64_b32 v[62:63], v16 offset0:108 offset1:110
	ds_read2st64_b32 v[64:65], v16 offset0:112 offset1:114
	ds_read2st64_b32 v[66:67], v16 offset0:116 offset1:118
	ds_read2st64_b32 v[68:69], v16 offset0:120 offset1:122
	s_waitcnt lgkmcnt(7)
	ds_read2st64_b32 v[70:71], v16 offset0:124 offset1:126
	s_waitcnt lgkmcnt(0)
	ds_read_b128 v[24:27], v17 offset:256
	ds_read_b128 v[28:31], v17 offset:512
	ds_read_b128 v[32:35], v17 offset:768
	ds_read_b128 v[36:39], v17 offset:1024
	ds_read_b128 v[40:43], v17 offset:1280
	ds_read_b128 v[44:47], v17 offset:1296
	ds_read_b128 v[48:51], v17 offset:1536
	ds_read_b128 v[52:55], v17 offset:1552
	ds_read_b128 v[56:59], v17 offset:1792
	ds_read_b128 v[4:7], v17 offset:1808
	ds_read_b128 v[8:11], v17 offset:2048
	ds_read_b128 v[12:15], v17 offset:2064
	s_waitcnt lgkmcnt(10)
	v_mul_f32_e64 v72, -v24, v92
	ds_read_b128 v[24:27], v17 offset:2304
	v_add_f32_e32 v93, v93, v72
	v_mul_f32_e64 v72, -v28, v92
	v_mul_f32_e64 v73, -v29, v93
	ds_read_b128 v[28:31], v17 offset:2320
	v_add_f32_e32 v72, v72, v73
	v_add_f32_e32 v94, v94, v72
	s_waitcnt lgkmcnt(10)
	v_mul_f32_e64 v72, -v32, v92
	v_mul_f32_e64 v73, -v33, v93
	v_mul_f32_e64 v74, -v34, v94
	ds_read_b128 v[32:35], v17 offset:2336
	v_add_f32_e32 v72, v72, v73
	v_add_f32_e32 v95, v95, v74
	v_add_f32_e32 v95, v95, v72
	v_mul_f32_e64 v72, -v36, v92
	v_mul_f32_e64 v73, -v37, v93
	v_mul_f32_e64 v74, -v38, v94
	v_mul_f32_e64 v75, -v39, v95
	ds_read_b128 v[36:39], v17 offset:2560
	v_add_f32_e32 v72, v72, v73
	v_add_f32_e32 v74, v74, v75
	v_add_f32_e32 v96, v96, v72
	v_add_f32_e32 v96, v96, v74
	s_waitcnt lgkmcnt(10)
	v_mul_f32_e64 v72, -v40, v92
	v_mul_f32_e64 v73, -v41, v93
	v_mul_f32_e64 v74, -v42, v94
	v_mul_f32_e64 v75, -v43, v95
	ds_read_b128 v[40:43], v17 offset:2576
	v_fma_f32 v72, -v44, v96, v72
	ds_read_b128 v[44:47], v17 offset:2592
	v_add_f32_e32 v72, v72, v73
	v_add_f32_e32 v74, v74, v75
	v_add_f32_e32 v97, v97, v72
	v_add_f32_e32 v97, v97, v74
	s_waitcnt lgkmcnt(10)
	v_mul_f32_e64 v72, -v48, v92
	v_mul_f32_e64 v73, -v49, v93
	v_mul_f32_e64 v74, -v50, v94
	v_mul_f32_e64 v75, -v51, v95
	ds_read_b128 v[48:51], v17 offset:2816
	v_fma_f32 v72, -v52, v96, v72
	v_fma_f32 v73, -v53, v97, v73
	ds_read_b128 v[52:55], v17 offset:2832
	v_add_f32_e32 v72, v72, v73
	v_add_f32_e32 v74, v74, v75
	v_add_f32_e32 v98, v98, v72
	v_add_f32_e32 v98, v98, v74
	s_waitcnt lgkmcnt(10)
	v_mul_f32_e64 v72, -v56, v92
	v_mul_f32_e64 v73, -v57, v93
	v_mul_f32_e64 v74, -v58, v94
	v_mul_f32_e64 v75, -v59, v95
	ds_read_b128 v[56:59], v17 offset:2848
	v_fma_f32 v72, -v4, v96, v72
	v_fma_f32 v73, -v5, v97, v73
	v_fma_f32 v74, -v6, v98, v74
	ds_read_b128 v[4:7], v17 offset:3072
	v_add_f32_e32 v72, v72, v73
	v_add_f32_e32 v74, v74, v75
	v_add_f32_e32 v99, v99, v72
	v_add_f32_e32 v99, v99, v74
	s_waitcnt lgkmcnt(10)
	v_mul_f32_e64 v72, -v8, v92
	v_mul_f32_e64 v73, -v9, v93
	v_mul_f32_e64 v74, -v10, v94
	v_mul_f32_e64 v75, -v11, v95
	ds_read_b128 v[8:11], v17 offset:3088
	v_fma_f32 v72, -v12, v96, v72
	v_fma_f32 v73, -v13, v97, v73
	v_fma_f32 v74, -v14, v98, v74
	v_fma_f32 v75, -v15, v99, v75
	ds_read_b128 v[12:15], v17 offset:3104
	v_add_f32_e32 v72, v72, v73
	v_add_f32_e32 v74, v74, v75
	v_add_f32_e32 v100, v100, v72
	v_add_f32_e32 v100, v100, v74
	s_waitcnt lgkmcnt(10)
	v_mul_f32_e64 v72, -v24, v92
	v_mul_f32_e64 v73, -v25, v93
	v_mul_f32_e64 v74, -v26, v94
	v_mul_f32_e64 v75, -v27, v95
	ds_read_b128 v[24:27], v17 offset:3328
	v_fma_f32 v72, -v28, v96, v72
	v_fma_f32 v73, -v29, v97, v73
	v_fma_f32 v74, -v30, v98, v74
	v_fma_f32 v75, -v31, v99, v75
	ds_read_b128 v[28:31], v17 offset:3344
	s_waitcnt lgkmcnt(10)
; #define LAS __attribute__((address_space(3)))
; __device__ __forceinline__ void even_prep(const Ctx& c, const Params& p, int e) {
;     ...
;             for (int i = 1; i < 64; ++i) { const LAS f32x4* Lr = (const LAS f32x4*)(Lv + i * 64); float a0 = x[i], a1 = 0.f;
; #pragma unroll
;                 for (int j4 = 0; j4 < (i + 3) / 4; ++j4) { const f32x4 l = Lr[j4];
;                     if (4 * j4 + 0 < i) a0 -= l[0] * x[4 * j4 + 0];
;                     if (4 * j4 + 1 < i) a1 -= l[1] * x[4 * j4 + 1];
;                     if (4 * j4 + 2 < i) a0 -= l[2] * x[4 * j4 + 2];
;                     if (4 * j4 + 3 < i) a1 -= l[3] * x[4 * j4 + 3]; }
;                 x[i] = a0 + a1; }
	v_fma_f32 v72, -v32, v100, v72
	ds_read_b128 v[32:35], v17 offset:3360
	v_add_f32_e32 v72, v72, v73
	v_add_f32_e32 v74, v74, v75
	v_add_f32_e32 v101, v101, v72
	v_add_f32_e32 v101, v101, v74
	v_mul_f32_e64 v72, -v36, v92
	v_mul_f32_e64 v73, -v37, v93
	v_mul_f32_e64 v74, -v38, v94
	v_mul_f32_e64 v75, -v39, v95
	ds_read_b128 v[36:39], v17 offset:3376
	s_waitcnt lgkmcnt(10)
	v_fma_f32 v72, -v40, v96, v72
	v_fma_f32 v73, -v41, v97, v73
	v_fma_f32 v74, -v42, v98, v74
	v_fma_f32 v75, -v43, v99, v75
	ds_read_b128 v[40:43], v17 offset:3584
	v_fma_f32 v72, -v44, v100, v72
	v_fma_f32 v73, -v45, v101, v73
	ds_read_b128 v[44:47], v17 offset:3600
	v_add_f32_e32 v72, v72, v73
	v_add_f32_e32 v74, v74, v75
	v_add_f32_e32 v102, v102, v72
	v_add_f32_e32 v102, v102, v74
	s_waitcnt lgkmcnt(10)
	v_mul_f32_e64 v72, -v48, v92
	v_mul_f32_e64 v73, -v49, v93
	v_mul_f32_e64 v74, -v50, v94
	v_mul_f32_e64 v75, -v51, v95
	ds_read_b128 v[48:51], v17 offset:3616
	v_fma_f32 v72, -v52, v96, v72
	v_fma_f32 v73, -v53, v97, v73
	v_fma_f32 v74, -v54, v98, v74
	v_fma_f32 v75, -v55, v99, v75
	ds_read_b128 v[52:55], v17 offset:3632
	s_waitcnt lgkmcnt(10)
	v_fma_f32 v72, -v56, v100, v72
	v_fma_f32 v73, -v57, v101, v73
	v_fma_f32 v74, -v58, v102, v74
	ds_read_b128 v[56:59], v17 offset:3840
	v_add_f32_e32 v72, v72, v73
	v_add_f32_e32 v74, v74, v75
	v_add_f32_e32 v103, v103, v72
	v_add_f32_e32 v103, v103, v74
	v_mul_f32_e64 v72, -v4, v92
	v_mul_f32_e64 v73, -v5, v93
	v_mul_f32_e64 v74, -v6, v94
	v_mul_f32_e64 v75, -v7, v95
	ds_read_b128 v[4:7], v17 offset:3856
	s_waitcnt lgkmcnt(10)
	v_fma_f32 v72, -v8, v96, v72
	v_fma_f32 v73, -v9, v97, v73
	v_fma_f32 v74, -v10, v98, v74
	v_fma_f32 v75, -v11, v99, v75
	ds_read_b128 v[8:11], v17 offset:3872
	v_fma_f32 v72, -v12, v100, v72
	v_fma_f32 v73, -v13, v101, v73
	v_fma_f32 v74, -v14, v102, v74
	v_fma_f32 v75, -v15, v103, v75
	ds_read_b128 v[12:15], v17 offset:3888
	v_add_f32_e32 v72, v72, v73
	v_add_f32_e32 v74, v74, v75
	v_add_f32_e32 v104, v104, v72
	v_add_f32_e32 v104, v104, v74
	s_waitcnt lgkmcnt(10)
	v_mul_f32_e64 v72, -v24, v92
	v_mul_f32_e64 v73, -v25, v93
	v_mul_f32_e64 v74, -v26, v94
	v_mul_f32_e64 v75, -v27, v95
	ds_read_b128 v[24:27], v17 offset:4096
	v_fma_f32 v72, -v28, v96, v72
	v_fma_f32 v73, -v29, v97, v73
	v_fma_f32 v74, -v30, v98, v74
	v_fma_f32 v75, -v31, v99, v75
	ds_read_b128 v[28:31], v17 offset:4112
	s_waitcnt lgkmcnt(10)
	v_fma_f32 v72, -v32, v100, v72
	v_fma_f32 v73, -v33, v101, v73
	v_fma_f32 v74, -v34, v102, v74
	v_fma_f32 v75, -v35, v103, v75
	ds_read_b128 v[32:35], v17 offset:4128
	v_fma_f32 v72, -v36, v104, v72
	ds_read_b128 v[36:39], v17 offset:4144
	v_add_f32_e32 v72, v72, v73
	v_add_f32_e32 v74, v74, v75
	v_add_f32_e32 v105, v105, v72
	v_add_f32_e32 v105, v105, v74
	s_waitcnt lgkmcnt(10)
	v_mul_f32_e64 v72, -v40, v92
	v_mul_f32_e64 v73, -v41, v93
	v_mul_f32_e64 v74, -v42, v94
	v_mul_f32_e64 v75, -v43, v95
	ds_read_b128 v[40:43], v17 offset:4352
	v_fma_f32 v72, -v44, v96, v72
	v_fma_f32 v73, -v45, v97, v73
	v_fma_f32 v74, -v46, v98, v74
	v_fma_f32 v75, -v47, v99, v75
	ds_read_b128 v[44:47], v17 offset:4368
	s_waitcnt lgkmcnt(10)
	v_fma_f32 v72, -v48, v100, v72
	v_fma_f32 v73, -v49, v101, v73
	v_fma_f32 v74, -v50, v102, v74
	v_fma_f32 v75, -v51, v103, v75
	ds_read_b128 v[48:51], v17 offset:4384
	v_fma_f32 v72, -v52, v104, v72
	v_fma_f32 v73, -v53, v105, v73
	ds_read_b128 v[52:55], v17 offset:4400
	v_add_f32_e32 v72, v72, v73
	v_add_f32_e32 v74, v74, v75
	v_add_f32_e32 v106, v106, v72
	v_add_f32_e32 v106, v106, v74
	s_waitcnt lgkmcnt(10)
	v_mul_f32_e64 v72, -v56, v92
	v_mul_f32_e64 v73, -v57, v93
	v_mul_f32_e64 v74, -v58, v94
	v_mul_f32_e64 v75, -v59, v95
	ds_read_b128 v[56:59], v17 offset:4416
	v_fma_f32 v72, -v4, v96, v72
	v_fma_f32 v73, -v5, v97, v73
	v_fma_f32 v74, -v6, v98, v74
	v_fma_f32 v75, -v7, v99, v75
	ds_read_b128 v[4:7], v17 offset:4608
	s_waitcnt lgkmcnt(10)
	v_fma_f32 v72, -v8, v100, v72
	v_fma_f32 v73, -v9, v101, v73
	v_fma_f32 v74, -v10, v102, v74
	v_fma_f32 v75, -v11, v103, v75
	ds_read_b128 v[8:11], v17 offset:4624
	v_fma_f32 v72, -v12, v104, v72
	v_fma_f32 v73, -v13, v105, v73
	v_fma_f32 v74, -v14, v106, v74
	ds_read_b128 v[12:15], v17 offset:4640
	v_add_f32_e32 v72, v72, v73
	v_add_f32_e32 v74, v74, v75
	v_add_f32_e32 v107, v107, v72
	v_add_f32_e32 v107, v107, v74
	s_waitcnt lgkmcnt(10)
	v_mul_f32_e64 v72, -v24, v92
	v_mul_f32_e64 v73, -v25, v93
	v_mul_f32_e64 v74, -v26, v94
	v_mul_f32_e64 v75, -v27, v95
	ds_read_b128 v[24:27], v17 offset:4656
	v_fma_f32 v72, -v28, v96, v72
	v_fma_f32 v73, -v29, v97, v73
	v_fma_f32 v74, -v30, v98, v74
	v_fma_f32 v75, -v31, v99, v75
	ds_read_b128 v[28:31], v17 offset:4672
	s_waitcnt lgkmcnt(10)
	v_fma_f32 v72, -v32, v100, v72
	v_fma_f32 v73, -v33, v101, v73
	v_fma_f32 v74, -v34, v102, v74
	v_fma_f32 v75, -v35, v103, v75
	ds_read_b128 v[32:35], v17 offset:4864
	v_fma_f32 v72, -v36, v104, v72
	v_fma_f32 v73, -v37, v105, v73
	v_fma_f32 v74, -v38, v106, v74
	v_fma_f32 v75, -v39, v107, v75
	ds_read_b128 v[36:39], v17 offset:4880
	v_add_f32_e32 v72, v72, v73
	v_add_f32_e32 v74, v74, v75
	v_add_f32_e32 v108, v108, v72
	v_add_f32_e32 v108, v108, v74
	s_waitcnt lgkmcnt(10)
	v_mul_f32_e64 v72, -v40, v92
	v_mul_f32_e64 v73, -v41, v93
	v_mul_f32_e64 v74, -v42, v94
	v_mul_f32_e64 v75, -v43, v95
	ds_read_b128 v[40:43], v17 offset:4896
	v_fma_f32 v72, -v44, v96, v72
	v_fma_f32 v73, -v45, v97, v73
	v_fma_f32 v74, -v46, v98, v74
	v_fma_f32 v75, -v47, v99, v75
	ds_read_b128 v[44:47], v17 offset:4912
	s_waitcnt lgkmcnt(10)
; #define LAS __attribute__((address_space(3)))
; __device__ __forceinline__ void even_prep(const Ctx& c, const Params& p, int e) {
;     ...
;             for (int i = 1; i < 64; ++i) { const LAS f32x4* Lr = (const LAS f32x4*)(Lv + i * 64); float a0 = x[i], a1 = 0.f;
; #pragma unroll
;                 for (int j4 = 0; j4 < (i + 3) / 4; ++j4) { const f32x4 l = Lr[j4];
;                     if (4 * j4 + 0 < i) a0 -= l[0] * x[4 * j4 + 0];
;                     if (4 * j4 + 1 < i) a1 -= l[1] * x[4 * j4 + 1];
;                     if (4 * j4 + 2 < i) a0 -= l[2] * x[4 * j4 + 2];
;                     if (4 * j4 + 3 < i) a1 -= l[3] * x[4 * j4 + 3]; }
;                 x[i] = a0 + a1; }
	v_fma_f32 v72, -v48, v100, v72
	v_fma_f32 v73, -v49, v101, v73
	v_fma_f32 v74, -v50, v102, v74
	v_fma_f32 v75, -v51, v103, v75
	ds_read_b128 v[48:51], v17 offset:4928
	v_fma_f32 v72, -v52, v104, v72
	v_fma_f32 v73, -v53, v105, v73
	v_fma_f32 v74, -v54, v106, v74
	v_fma_f32 v75, -v55, v107, v75
	ds_read_b128 v[52:55], v17 offset:5120
	s_waitcnt lgkmcnt(10)
	v_fma_f32 v72, -v56, v108, v72
	ds_read_b128 v[56:59], v17 offset:5136
	v_add_f32_e32 v72, v72, v73
	v_add_f32_e32 v74, v74, v75
	v_add_f32_e32 v109, v109, v72
	v_add_f32_e32 v109, v109, v74
	v_mul_f32_e64 v72, -v4, v92
	v_mul_f32_e64 v73, -v5, v93
	v_mul_f32_e64 v74, -v6, v94
	v_mul_f32_e64 v75, -v7, v95
	ds_read_b128 v[4:7], v17 offset:5152
	s_waitcnt lgkmcnt(10)
	v_fma_f32 v72, -v8, v96, v72
	v_fma_f32 v73, -v9, v97, v73
	v_fma_f32 v74, -v10, v98, v74
	v_fma_f32 v75, -v11, v99, v75
	ds_read_b128 v[8:11], v17 offset:5168
	v_fma_f32 v72, -v12, v100, v72
	v_fma_f32 v73, -v13, v101, v73
	v_fma_f32 v74, -v14, v102, v74
	v_fma_f32 v75, -v15, v103, v75
	ds_read_b128 v[12:15], v17 offset:5184
	s_waitcnt lgkmcnt(10)
	v_fma_f32 v72, -v24, v104, v72
	v_fma_f32 v73, -v25, v105, v73
	v_fma_f32 v74, -v26, v106, v74
	v_fma_f32 v75, -v27, v107, v75
	ds_read_b128 v[24:27], v17 offset:5376
	v_fma_f32 v72, -v28, v108, v72
	v_fma_f32 v73, -v29, v109, v73
	ds_read_b128 v[28:31], v17 offset:5392
	v_add_f32_e32 v72, v72, v73
	v_add_f32_e32 v74, v74, v75
	v_add_f32_e32 v110, v110, v72
	v_add_f32_e32 v110, v110, v74
	s_waitcnt lgkmcnt(10)
	v_mul_f32_e64 v72, -v32, v92
	v_mul_f32_e64 v73, -v33, v93
	v_mul_f32_e64 v74, -v34, v94
	v_mul_f32_e64 v75, -v35, v95
	ds_read_b128 v[32:35], v17 offset:5408
	v_fma_f32 v72, -v36, v96, v72
	v_fma_f32 v73, -v37, v97, v73
	v_fma_f32 v74, -v38, v98, v74
	v_fma_f32 v75, -v39, v99, v75
	ds_read_b128 v[36:39], v17 offset:5424
	s_waitcnt lgkmcnt(10)
	v_fma_f32 v72, -v40, v100, v72
	v_fma_f32 v73, -v41, v101, v73
	v_fma_f32 v74, -v42, v102, v74
	v_fma_f32 v75, -v43, v103, v75
	ds_read_b128 v[40:43], v17 offset:5440
	v_fma_f32 v72, -v44, v104, v72
	v_fma_f32 v73, -v45, v105, v73
	v_fma_f32 v74, -v46, v106, v74
	v_fma_f32 v75, -v47, v107, v75
	ds_read_b128 v[44:47], v17 offset:5456
	s_waitcnt lgkmcnt(10)
	v_fma_f32 v72, -v48, v108, v72
	v_fma_f32 v73, -v49, v109, v73
	v_fma_f32 v74, -v50, v110, v74
	ds_read_b128 v[48:51], v17 offset:5632
	v_add_f32_e32 v72, v72, v73
	v_add_f32_e32 v74, v74, v75
	v_add_f32_e32 v111, v111, v72
	v_add_f32_e32 v111, v111, v74
	v_mul_f32_e64 v72, -v52, v92
	v_mul_f32_e64 v73, -v53, v93
	v_mul_f32_e64 v74, -v54, v94
	v_mul_f32_e64 v75, -v55, v95
	ds_read_b128 v[52:55], v17 offset:5648
	s_waitcnt lgkmcnt(10)
	v_fma_f32 v72, -v56, v96, v72
	v_fma_f32 v73, -v57, v97, v73
	v_fma_f32 v74, -v58, v98, v74
	v_fma_f32 v75, -v59, v99, v75
	ds_read_b128 v[56:59], v17 offset:5664
	v_fma_f32 v72, -v4, v100, v72
	v_fma_f32 v73, -v5, v101, v73
	v_fma_f32 v74, -v6, v102, v74
	v_fma_f32 v75, -v7, v103, v75
	ds_read_b128 v[4:7], v17 offset:5680
	s_waitcnt lgkmcnt(10)
	v_fma_f32 v72, -v8, v104, v72
	v_fma_f32 v73, -v9, v105, v73
	v_fma_f32 v74, -v10, v106, v74
	v_fma_f32 v75, -v11, v107, v75
	ds_read_b128 v[8:11], v17 offset:5696
	v_fma_f32 v72, -v12, v108, v72
	v_fma_f32 v73, -v13, v109, v73
	v_fma_f32 v74, -v14, v110, v74
	v_fma_f32 v75, -v15, v111, v75
	ds_read_b128 v[12:15], v17 offset:5712
	v_add_f32_e32 v72, v72, v73
	v_add_f32_e32 v74, v74, v75
	v_add_f32_e32 v112, v112, v72
	v_add_f32_e32 v112, v112, v74
	s_waitcnt lgkmcnt(10)
	v_mul_f32_e64 v72, -v24, v92
	v_mul_f32_e64 v73, -v25, v93
	v_mul_f32_e64 v74, -v26, v94
	v_mul_f32_e64 v75, -v27, v95
	ds_read_b128 v[24:27], v17 offset:5888
	v_fma_f32 v72, -v28, v96, v72
	v_fma_f32 v73, -v29, v97, v73
	v_fma_f32 v74, -v30, v98, v74
	v_fma_f32 v75, -v31, v99, v75
	ds_read_b128 v[28:31], v17 offset:5904
	s_waitcnt lgkmcnt(10)
	v_fma_f32 v72, -v32, v100, v72
	v_fma_f32 v73, -v33, v101, v73
	v_fma_f32 v74, -v34, v102, v74
	v_fma_f32 v75, -v35, v103, v75
	ds_read_b128 v[32:35], v17 offset:5920
	v_fma_f32 v72, -v36, v104, v72
	v_fma_f32 v73, -v37, v105, v73
	v_fma_f32 v74, -v38, v106, v74
	v_fma_f32 v75, -v39, v107, v75
	ds_read_b128 v[36:39], v17 offset:5936
	s_waitcnt lgkmcnt(10)
	v_fma_f32 v72, -v40, v108, v72
	v_fma_f32 v73, -v41, v109, v73
	v_fma_f32 v74, -v42, v110, v74
	v_fma_f32 v75, -v43, v111, v75
	ds_read_b128 v[40:43], v17 offset:5952
	v_fma_f32 v72, -v44, v112, v72
	ds_read_b128 v[44:47], v17 offset:5968
	v_add_f32_e32 v72, v72, v73
	v_add_f32_e32 v74, v74, v75
	v_add_f32_e32 v113, v113, v72
	v_add_f32_e32 v113, v113, v74
	s_waitcnt lgkmcnt(10)
	v_mul_f32_e64 v72, -v48, v92
	v_mul_f32_e64 v73, -v49, v93
	v_mul_f32_e64 v74, -v50, v94
	v_mul_f32_e64 v75, -v51, v95
	ds_read_b128 v[48:51], v17 offset:6144
	v_fma_f32 v72, -v52, v96, v72
	v_fma_f32 v73, -v53, v97, v73
	v_fma_f32 v74, -v54, v98, v74
	v_fma_f32 v75, -v55, v99, v75
	ds_read_b128 v[52:55], v17 offset:6160
	s_waitcnt lgkmcnt(10)
	v_fma_f32 v72, -v56, v100, v72
	v_fma_f32 v73, -v57, v101, v73
	v_fma_f32 v74, -v58, v102, v74
	v_fma_f32 v75, -v59, v103, v75
	ds_read_b128 v[56:59], v17 offset:6176
	v_fma_f32 v72, -v4, v104, v72
	v_fma_f32 v73, -v5, v105, v73
	v_fma_f32 v74, -v6, v106, v74
	v_fma_f32 v75, -v7, v107, v75
	ds_read_b128 v[4:7], v17 offset:6192
	s_waitcnt lgkmcnt(10)
	v_fma_f32 v72, -v8, v108, v72
	v_fma_f32 v73, -v9, v109, v73
	v_fma_f32 v74, -v10, v110, v74
	v_fma_f32 v75, -v11, v111, v75
	ds_read_b128 v[8:11], v17 offset:6208
	v_fma_f32 v72, -v12, v112, v72
	v_fma_f32 v73, -v13, v113, v73
	ds_read_b128 v[12:15], v17 offset:6224
	v_add_f32_e32 v72, v72, v73
	v_add_f32_e32 v74, v74, v75
	v_add_f32_e32 v114, v114, v72
	v_add_f32_e32 v114, v114, v74
	s_waitcnt lgkmcnt(10)
; #define LAS __attribute__((address_space(3)))
; __device__ __forceinline__ void even_prep(const Ctx& c, const Params& p, int e) {
;     ...
;             for (int i = 1; i < 64; ++i) { const LAS f32x4* Lr = (const LAS f32x4*)(Lv + i * 64); float a0 = x[i], a1 = 0.f;
; #pragma unroll
;                 for (int j4 = 0; j4 < (i + 3) / 4; ++j4) { const f32x4 l = Lr[j4];
;                     if (4 * j4 + 0 < i) a0 -= l[0] * x[4 * j4 + 0];
;                     if (4 * j4 + 1 < i) a1 -= l[1] * x[4 * j4 + 1];
;                     if (4 * j4 + 2 < i) a0 -= l[2] * x[4 * j4 + 2];
;                     if (4 * j4 + 3 < i) a1 -= l[3] * x[4 * j4 + 3]; }
;                 x[i] = a0 + a1; }
	v_mul_f32_e64 v72, -v24, v92
	v_mul_f32_e64 v73, -v25, v93
	v_mul_f32_e64 v74, -v26, v94
	v_mul_f32_e64 v75, -v27, v95
	ds_read_b128 v[24:27], v17 offset:6400
	v_fma_f32 v72, -v28, v96, v72
	v_fma_f32 v73, -v29, v97, v73
	v_fma_f32 v74, -v30, v98, v74
	v_fma_f32 v75, -v31, v99, v75
	ds_read_b128 v[28:31], v17 offset:6416
	s_waitcnt lgkmcnt(10)
	v_fma_f32 v72, -v32, v100, v72
	v_fma_f32 v73, -v33, v101, v73
	v_fma_f32 v74, -v34, v102, v74
	v_fma_f32 v75, -v35, v103, v75
	ds_read_b128 v[32:35], v17 offset:6432
	v_fma_f32 v72, -v36, v104, v72
	v_fma_f32 v73, -v37, v105, v73
	v_fma_f32 v74, -v38, v106, v74
	v_fma_f32 v75, -v39, v107, v75
	ds_read_b128 v[36:39], v17 offset:6448
	s_waitcnt lgkmcnt(10)
	v_fma_f32 v72, -v40, v108, v72
	v_fma_f32 v73, -v41, v109, v73
	v_fma_f32 v74, -v42, v110, v74
	v_fma_f32 v75, -v43, v111, v75
	ds_read_b128 v[40:43], v17 offset:6464
	v_fma_f32 v72, -v44, v112, v72
	v_fma_f32 v73, -v45, v113, v73
	v_fma_f32 v74, -v46, v114, v74
	ds_read_b128 v[44:47], v17 offset:6480
	v_add_f32_e32 v72, v72, v73
	v_add_f32_e32 v74, v74, v75
	v_add_f32_e32 v115, v115, v72
	v_add_f32_e32 v115, v115, v74
	s_waitcnt lgkmcnt(10)
	v_mul_f32_e64 v72, -v48, v92
	v_mul_f32_e64 v73, -v49, v93
	v_mul_f32_e64 v74, -v50, v94
	v_mul_f32_e64 v75, -v51, v95
	ds_read_b128 v[48:51], v17 offset:6496
	v_fma_f32 v72, -v52, v96, v72
	v_fma_f32 v73, -v53, v97, v73
	v_fma_f32 v74, -v54, v98, v74
	v_fma_f32 v75, -v55, v99, v75
	ds_read_b128 v[52:55], v17 offset:6656
	s_waitcnt lgkmcnt(10)
	v_fma_f32 v72, -v56, v100, v72
	v_fma_f32 v73, -v57, v101, v73
	v_fma_f32 v74, -v58, v102, v74
	v_fma_f32 v75, -v59, v103, v75
	ds_read_b128 v[56:59], v17 offset:6672
	v_fma_f32 v72, -v4, v104, v72
	v_fma_f32 v73, -v5, v105, v73
	v_fma_f32 v74, -v6, v106, v74
	v_fma_f32 v75, -v7, v107, v75
	ds_read_b128 v[4:7], v17 offset:6688
	s_waitcnt lgkmcnt(10)
	v_fma_f32 v72, -v8, v108, v72
	v_fma_f32 v73, -v9, v109, v73
	v_fma_f32 v74, -v10, v110, v74
	v_fma_f32 v75, -v11, v111, v75
	ds_read_b128 v[8:11], v17 offset:6704
	v_fma_f32 v72, -v12, v112, v72
	v_fma_f32 v73, -v13, v113, v73
	v_fma_f32 v74, -v14, v114, v74
	v_fma_f32 v75, -v15, v115, v75
	ds_read_b128 v[12:15], v17 offset:6720
	v_add_f32_e32 v72, v72, v73
	v_add_f32_e32 v74, v74, v75
	v_add_f32_e32 v116, v116, v72
	v_add_f32_e32 v116, v116, v74
	s_waitcnt lgkmcnt(10)
	v_mul_f32_e64 v72, -v24, v92
	v_mul_f32_e64 v73, -v25, v93
	v_mul_f32_e64 v74, -v26, v94
	v_mul_f32_e64 v75, -v27, v95
	ds_read_b128 v[24:27], v17 offset:6736
	v_fma_f32 v72, -v28, v96, v72
	v_fma_f32 v73, -v29, v97, v73
	v_fma_f32 v74, -v30, v98, v74
	v_fma_f32 v75, -v31, v99, v75
	ds_read_b128 v[28:31], v17 offset:6752
	s_waitcnt lgkmcnt(10)
	v_fma_f32 v72, -v32, v100, v72
	v_fma_f32 v73, -v33, v101, v73
	v_fma_f32 v74, -v34, v102, v74
	v_fma_f32 v75, -v35, v103, v75
	ds_read_b128 v[32:35], v17 offset:6912
	v_fma_f32 v72, -v36, v104, v72
	v_fma_f32 v73, -v37, v105, v73
	v_fma_f32 v74, -v38, v106, v74
	v_fma_f32 v75, -v39, v107, v75
	ds_read_b128 v[36:39], v17 offset:6928
	s_waitcnt lgkmcnt(10)
	v_fma_f32 v72, -v40, v108, v72
	v_fma_f32 v73, -v41, v109, v73
	v_fma_f32 v74, -v42, v110, v74
	v_fma_f32 v75, -v43, v111, v75
	ds_read_b128 v[40:43], v17 offset:6944
	v_fma_f32 v72, -v44, v112, v72
	v_fma_f32 v73, -v45, v113, v73
	v_fma_f32 v74, -v46, v114, v74
	v_fma_f32 v75, -v47, v115, v75
	ds_read_b128 v[44:47], v17 offset:6960
	s_waitcnt lgkmcnt(10)
	v_fma_f32 v72, -v48, v116, v72
	ds_read_b128 v[48:51], v17 offset:6976
	v_add_f32_e32 v72, v72, v73
	v_add_f32_e32 v74, v74, v75
	v_add_f32_e32 v117, v117, v72
	v_add_f32_e32 v117, v117, v74
	v_mul_f32_e64 v72, -v52, v92
	v_mul_f32_e64 v73, -v53, v93
	v_mul_f32_e64 v74, -v54, v94
	v_mul_f32_e64 v75, -v55, v95
	ds_read_b128 v[52:55], v17 offset:6992
	s_waitcnt lgkmcnt(10)
	v_fma_f32 v72, -v56, v96, v72
	v_fma_f32 v73, -v57, v97, v73
	v_fma_f32 v74, -v58, v98, v74
	v_fma_f32 v75, -v59, v99, v75
	ds_read_b128 v[56:59], v17 offset:7008
	v_fma_f32 v72, -v4, v100, v72
	v_fma_f32 v73, -v5, v101, v73
	v_fma_f32 v74, -v6, v102, v74
	v_fma_f32 v75, -v7, v103, v75
	ds_read_b128 v[4:7], v17 offset:7168
	s_waitcnt lgkmcnt(10)
	v_fma_f32 v72, -v8, v104, v72
	v_fma_f32 v73, -v9, v105, v73
	v_fma_f32 v74, -v10, v106, v74
	v_fma_f32 v75, -v11, v107, v75
	ds_read_b128 v[8:11], v17 offset:7184
	v_fma_f32 v72, -v12, v108, v72
	v_fma_f32 v73, -v13, v109, v73
	v_fma_f32 v74, -v14, v110, v74
	v_fma_f32 v75, -v15, v111, v75
	ds_read_b128 v[12:15], v17 offset:7200
	s_waitcnt lgkmcnt(10)
	v_fma_f32 v72, -v24, v112, v72
	v_fma_f32 v73, -v25, v113, v73
	v_fma_f32 v74, -v26, v114, v74
	v_fma_f32 v75, -v27, v115, v75
	ds_read_b128 v[24:27], v17 offset:7216
	v_fma_f32 v72, -v28, v116, v72
	v_fma_f32 v73, -v29, v117, v73
	ds_read_b128 v[28:31], v17 offset:7232
	v_add_f32_e32 v72, v72, v73
	v_add_f32_e32 v74, v74, v75
	v_add_f32_e32 v118, v118, v72
	v_add_f32_e32 v118, v118, v74
	s_waitcnt lgkmcnt(10)
	v_mul_f32_e64 v72, -v32, v92
	v_mul_f32_e64 v73, -v33, v93
	v_mul_f32_e64 v74, -v34, v94
	v_mul_f32_e64 v75, -v35, v95
	ds_read_b128 v[32:35], v17 offset:7248
	v_fma_f32 v72, -v36, v96, v72
	v_fma_f32 v73, -v37, v97, v73
	v_fma_f32 v74, -v38, v98, v74
	v_fma_f32 v75, -v39, v99, v75
	ds_read_b128 v[36:39], v17 offset:7264
	s_waitcnt lgkmcnt(10)
	v_fma_f32 v72, -v40, v100, v72
	v_fma_f32 v73, -v41, v101, v73
	v_fma_f32 v74, -v42, v102, v74
	v_fma_f32 v75, -v43, v103, v75
	ds_read_b128 v[40:43], v17 offset:7424
	v_fma_f32 v72, -v44, v104, v72
	v_fma_f32 v73, -v45, v105, v73
	v_fma_f32 v74, -v46, v106, v74
	v_fma_f32 v75, -v47, v107, v75
	ds_read_b128 v[44:47], v17 offset:7440
	s_waitcnt lgkmcnt(10)
; #define LAS __attribute__((address_space(3)))
; __device__ __forceinline__ void even_prep(const Ctx& c, const Params& p, int e) {
;     ...
;             for (int i = 1; i < 64; ++i) { const LAS f32x4* Lr = (const LAS f32x4*)(Lv + i * 64); float a0 = x[i], a1 = 0.f;
; #pragma unroll
;                 for (int j4 = 0; j4 < (i + 3) / 4; ++j4) { const f32x4 l = Lr[j4];
;                     if (4 * j4 + 0 < i) a0 -= l[0] * x[4 * j4 + 0];
;                     if (4 * j4 + 1 < i) a1 -= l[1] * x[4 * j4 + 1];
;                     if (4 * j4 + 2 < i) a0 -= l[2] * x[4 * j4 + 2];
;                     if (4 * j4 + 3 < i) a1 -= l[3] * x[4 * j4 + 3]; }
;                 x[i] = a0 + a1; }
	v_fma_f32 v72, -v48, v108, v72
	v_fma_f32 v73, -v49, v109, v73
	v_fma_f32 v74, -v50, v110, v74
	v_fma_f32 v75, -v51, v111, v75
	ds_read_b128 v[48:51], v17 offset:7456
	v_fma_f32 v72, -v52, v112, v72
	v_fma_f32 v73, -v53, v113, v73
	v_fma_f32 v74, -v54, v114, v74
	v_fma_f32 v75, -v55, v115, v75
	ds_read_b128 v[52:55], v17 offset:7472
	s_waitcnt lgkmcnt(10)
	v_fma_f32 v72, -v56, v116, v72
	v_fma_f32 v73, -v57, v117, v73
	v_fma_f32 v74, -v58, v118, v74
	ds_read_b128 v[56:59], v17 offset:7488
	v_add_f32_e32 v72, v72, v73
	v_add_f32_e32 v74, v74, v75
	v_add_f32_e32 v119, v119, v72
	v_add_f32_e32 v119, v119, v74
	v_mul_f32_e64 v72, -v4, v92
	v_mul_f32_e64 v73, -v5, v93
	v_mul_f32_e64 v74, -v6, v94
	v_mul_f32_e64 v75, -v7, v95
	ds_read_b128 v[4:7], v17 offset:7504
	s_waitcnt lgkmcnt(10)
	v_fma_f32 v72, -v8, v96, v72
	v_fma_f32 v73, -v9, v97, v73
	v_fma_f32 v74, -v10, v98, v74
	v_fma_f32 v75, -v11, v99, v75
	ds_read_b128 v[8:11], v17 offset:7520
	v_fma_f32 v72, -v12, v100, v72
	v_fma_f32 v73, -v13, v101, v73
	v_fma_f32 v74, -v14, v102, v74
	v_fma_f32 v75, -v15, v103, v75
	ds_read_b128 v[12:15], v17 offset:7536
	s_waitcnt lgkmcnt(10)
	v_fma_f32 v72, -v24, v104, v72
	v_fma_f32 v73, -v25, v105, v73
	v_fma_f32 v74, -v26, v106, v74
	v_fma_f32 v75, -v27, v107, v75
	ds_read_b128 v[24:27], v17 offset:7680
	v_fma_f32 v72, -v28, v108, v72
	v_fma_f32 v73, -v29, v109, v73
	v_fma_f32 v74, -v30, v110, v74
	v_fma_f32 v75, -v31, v111, v75
	ds_read_b128 v[28:31], v17 offset:7696
	s_waitcnt lgkmcnt(10)
	v_fma_f32 v72, -v32, v112, v72
	v_fma_f32 v73, -v33, v113, v73
	v_fma_f32 v74, -v34, v114, v74
	v_fma_f32 v75, -v35, v115, v75
	ds_read_b128 v[32:35], v17 offset:7712
	v_fma_f32 v72, -v36, v116, v72
	v_fma_f32 v73, -v37, v117, v73
	v_fma_f32 v74, -v38, v118, v74
	v_fma_f32 v75, -v39, v119, v75
	ds_read_b128 v[36:39], v17 offset:7728
	v_add_f32_e32 v72, v72, v73
	v_add_f32_e32 v74, v74, v75
	v_add_f32_e32 v120, v120, v72
	v_add_f32_e32 v120, v120, v74
	s_waitcnt lgkmcnt(10)
	v_mul_f32_e64 v72, -v40, v92
	v_mul_f32_e64 v73, -v41, v93
	v_mul_f32_e64 v74, -v42, v94
	v_mul_f32_e64 v75, -v43, v95
	ds_read_b128 v[40:43], v17 offset:7744
	v_fma_f32 v72, -v44, v96, v72
	v_fma_f32 v73, -v45, v97, v73
	v_fma_f32 v74, -v46, v98, v74
	v_fma_f32 v75, -v47, v99, v75
	ds_read_b128 v[44:47], v17 offset:7760
	s_waitcnt lgkmcnt(10)
	v_fma_f32 v72, -v48, v100, v72
	v_fma_f32 v73, -v49, v101, v73
	v_fma_f32 v74, -v50, v102, v74
	v_fma_f32 v75, -v51, v103, v75
	ds_read_b128 v[48:51], v17 offset:7776
	v_fma_f32 v72, -v52, v104, v72
	v_fma_f32 v73, -v53, v105, v73
	v_fma_f32 v74, -v54, v106, v74
	v_fma_f32 v75, -v55, v107, v75
	ds_read_b128 v[52:55], v17 offset:7792
	s_waitcnt lgkmcnt(10)
	v_fma_f32 v72, -v56, v108, v72
	v_fma_f32 v73, -v57, v109, v73
	v_fma_f32 v74, -v58, v110, v74
	v_fma_f32 v75, -v59, v111, v75
	ds_read_b128 v[56:59], v17 offset:7936
	v_fma_f32 v72, -v4, v112, v72
	v_fma_f32 v73, -v5, v113, v73
	v_fma_f32 v74, -v6, v114, v74
	v_fma_f32 v75, -v7, v115, v75
	ds_read_b128 v[4:7], v17 offset:7952
	s_waitcnt lgkmcnt(10)
	v_fma_f32 v72, -v8, v116, v72
	v_fma_f32 v73, -v9, v117, v73
	v_fma_f32 v74, -v10, v118, v74
	v_fma_f32 v75, -v11, v119, v75
	ds_read_b128 v[8:11], v17 offset:7968
	v_fma_f32 v72, -v12, v120, v72
	ds_read_b128 v[12:15], v17 offset:7984
	v_add_f32_e32 v72, v72, v73
	v_add_f32_e32 v74, v74, v75
	v_add_f32_e32 v121, v121, v72
	v_add_f32_e32 v121, v121, v74
	s_waitcnt lgkmcnt(10)
	v_mul_f32_e64 v72, -v24, v92
	v_mul_f32_e64 v73, -v25, v93
	v_mul_f32_e64 v74, -v26, v94
	v_mul_f32_e64 v75, -v27, v95
	ds_read_b128 v[24:27], v17 offset:8000
	v_fma_f32 v72, -v28, v96, v72
	v_fma_f32 v73, -v29, v97, v73
	v_fma_f32 v74, -v30, v98, v74
	v_fma_f32 v75, -v31, v99, v75
	ds_read_b128 v[28:31], v17 offset:8016
	s_waitcnt lgkmcnt(10)
	v_fma_f32 v72, -v32, v100, v72
	v_fma_f32 v73, -v33, v101, v73
	v_fma_f32 v74, -v34, v102, v74
	v_fma_f32 v75, -v35, v103, v75
	ds_read_b128 v[32:35], v17 offset:8032
	v_fma_f32 v72, -v36, v104, v72
	v_fma_f32 v73, -v37, v105, v73
	v_fma_f32 v74, -v38, v106, v74
	v_fma_f32 v75, -v39, v107, v75
	ds_read_b128 v[36:39], v17 offset:8048
	s_waitcnt lgkmcnt(10)
	v_fma_f32 v72, -v40, v108, v72
	v_fma_f32 v73, -v41, v109, v73
	v_fma_f32 v74, -v42, v110, v74
	v_fma_f32 v75, -v43, v111, v75
	ds_read_b128 v[40:43], v17 offset:8192
	v_fma_f32 v72, -v44, v112, v72
	v_fma_f32 v73, -v45, v113, v73
	v_fma_f32 v74, -v46, v114, v74
	v_fma_f32 v75, -v47, v115, v75
	ds_read_b128 v[44:47], v17 offset:8208
	s_waitcnt lgkmcnt(10)
	v_fma_f32 v72, -v48, v116, v72
	v_fma_f32 v73, -v49, v117, v73
	v_fma_f32 v74, -v50, v118, v74
	v_fma_f32 v75, -v51, v119, v75
	ds_read_b128 v[48:51], v17 offset:8224
	v_fma_f32 v72, -v52, v120, v72
	v_fma_f32 v73, -v53, v121, v73
	ds_read_b128 v[52:55], v17 offset:8240
	v_add_f32_e32 v72, v72, v73
	v_add_f32_e32 v74, v74, v75
	v_add_f32_e32 v122, v122, v72
	v_add_f32_e32 v122, v122, v74
	s_waitcnt lgkmcnt(10)
	v_mul_f32_e64 v72, -v56, v92
	v_mul_f32_e64 v73, -v57, v93
	v_mul_f32_e64 v74, -v58, v94
	v_mul_f32_e64 v75, -v59, v95
	ds_read_b128 v[56:59], v17 offset:8256
	v_fma_f32 v72, -v4, v96, v72
	v_fma_f32 v73, -v5, v97, v73
	v_fma_f32 v74, -v6, v98, v74
	v_fma_f32 v75, -v7, v99, v75
	ds_read_b128 v[4:7], v17 offset:8272
	s_waitcnt lgkmcnt(10)
	v_fma_f32 v72, -v8, v100, v72
	v_fma_f32 v73, -v9, v101, v73
	v_fma_f32 v74, -v10, v102, v74
	v_fma_f32 v75, -v11, v103, v75
	ds_read_b128 v[8:11], v17 offset:8288
	v_fma_f32 v72, -v12, v104, v72
	v_fma_f32 v73, -v13, v105, v73
	v_fma_f32 v74, -v14, v106, v74
	v_fma_f32 v75, -v15, v107, v75
	ds_read_b128 v[12:15], v17 offset:8304
	s_waitcnt lgkmcnt(10)
; #define LAS __attribute__((address_space(3)))
; __device__ __forceinline__ void even_prep(const Ctx& c, const Params& p, int e) {
;     ...
;             for (int i = 1; i < 64; ++i) { const LAS f32x4* Lr = (const LAS f32x4*)(Lv + i * 64); float a0 = x[i], a1 = 0.f;
; #pragma unroll
;                 for (int j4 = 0; j4 < (i + 3) / 4; ++j4) { const f32x4 l = Lr[j4];
;                     if (4 * j4 + 0 < i) a0 -= l[0] * x[4 * j4 + 0];
;                     if (4 * j4 + 1 < i) a1 -= l[1] * x[4 * j4 + 1];
;                     if (4 * j4 + 2 < i) a0 -= l[2] * x[4 * j4 + 2];
;                     if (4 * j4 + 3 < i) a1 -= l[3] * x[4 * j4 + 3]; }
;                 x[i] = a0 + a1; }
	v_fma_f32 v72, -v24, v108, v72
	v_fma_f32 v73, -v25, v109, v73
	v_fma_f32 v74, -v26, v110, v74
	v_fma_f32 v75, -v27, v111, v75
	ds_read_b128 v[24:27], v17 offset:8448
	v_fma_f32 v72, -v28, v112, v72
	v_fma_f32 v73, -v29, v113, v73
	v_fma_f32 v74, -v30, v114, v74
	v_fma_f32 v75, -v31, v115, v75
	ds_read_b128 v[28:31], v17 offset:8464
	s_waitcnt lgkmcnt(10)
	v_fma_f32 v72, -v32, v116, v72
	v_fma_f32 v73, -v33, v117, v73
	v_fma_f32 v74, -v34, v118, v74
	v_fma_f32 v75, -v35, v119, v75
	ds_read_b128 v[32:35], v17 offset:8480
	v_fma_f32 v72, -v36, v120, v72
	v_fma_f32 v73, -v37, v121, v73
	v_fma_f32 v74, -v38, v122, v74
	ds_read_b128 v[36:39], v17 offset:8496
	v_add_f32_e32 v72, v72, v73
	v_add_f32_e32 v74, v74, v75
	v_add_f32_e32 v123, v123, v72
	v_add_f32_e32 v123, v123, v74
	s_waitcnt lgkmcnt(10)
	v_mul_f32_e64 v72, -v40, v92
	v_mul_f32_e64 v73, -v41, v93
	v_mul_f32_e64 v74, -v42, v94
	v_mul_f32_e64 v75, -v43, v95
	ds_read_b128 v[40:43], v17 offset:8512
	v_fma_f32 v72, -v44, v96, v72
	v_fma_f32 v73, -v45, v97, v73
	v_fma_f32 v74, -v46, v98, v74
	v_fma_f32 v75, -v47, v99, v75
	ds_read_b128 v[44:47], v17 offset:8528
	s_waitcnt lgkmcnt(10)
	v_fma_f32 v72, -v48, v100, v72
	v_fma_f32 v73, -v49, v101, v73
	v_fma_f32 v74, -v50, v102, v74
	v_fma_f32 v75, -v51, v103, v75
	ds_read_b128 v[48:51], v17 offset:8544
	v_fma_f32 v72, -v52, v104, v72
	v_fma_f32 v73, -v53, v105, v73
	v_fma_f32 v74, -v54, v106, v74
	v_fma_f32 v75, -v55, v107, v75
	ds_read_b128 v[52:55], v17 offset:8560
	s_waitcnt lgkmcnt(10)
	v_fma_f32 v72, -v56, v108, v72
	v_fma_f32 v73, -v57, v109, v73
	v_fma_f32 v74, -v58, v110, v74
	v_fma_f32 v75, -v59, v111, v75
	ds_read_b128 v[56:59], v17 offset:8576
	v_fma_f32 v72, -v4, v112, v72
	v_fma_f32 v73, -v5, v113, v73
	v_fma_f32 v74, -v6, v114, v74
	v_fma_f32 v75, -v7, v115, v75
	ds_read_b128 v[4:7], v17 offset:8704
	s_waitcnt lgkmcnt(10)
	v_fma_f32 v72, -v8, v116, v72
	v_fma_f32 v73, -v9, v117, v73
	v_fma_f32 v74, -v10, v118, v74
	v_fma_f32 v75, -v11, v119, v75
	ds_read_b128 v[8:11], v17 offset:8720
	v_fma_f32 v72, -v12, v120, v72
	v_fma_f32 v73, -v13, v121, v73
	v_fma_f32 v74, -v14, v122, v74
	v_fma_f32 v75, -v15, v123, v75
	ds_read_b128 v[12:15], v17 offset:8736
	v_add_f32_e32 v72, v72, v73
	v_add_f32_e32 v74, v74, v75
	v_add_f32_e32 v124, v124, v72
	v_add_f32_e32 v124, v124, v74
	s_waitcnt lgkmcnt(10)
	v_mul_f32_e64 v72, -v24, v92
	v_mul_f32_e64 v73, -v25, v93
	v_mul_f32_e64 v74, -v26, v94
	v_mul_f32_e64 v75, -v27, v95
	ds_read_b128 v[24:27], v17 offset:8752
	v_fma_f32 v72, -v28, v96, v72
	v_fma_f32 v73, -v29, v97, v73
	v_fma_f32 v74, -v30, v98, v74
	v_fma_f32 v75, -v31, v99, v75
	ds_read_b128 v[28:31], v17 offset:8768
	s_waitcnt lgkmcnt(10)
	v_fma_f32 v72, -v32, v100, v72
	v_fma_f32 v73, -v33, v101, v73
	v_fma_f32 v74, -v34, v102, v74
	v_fma_f32 v75, -v35, v103, v75
	ds_read_b128 v[32:35], v17 offset:8784
	v_fma_f32 v72, -v36, v104, v72
	v_fma_f32 v73, -v37, v105, v73
	v_fma_f32 v74, -v38, v106, v74
	v_fma_f32 v75, -v39, v107, v75
	ds_read_b128 v[36:39], v17 offset:8800
	s_waitcnt lgkmcnt(10)
	v_fma_f32 v72, -v40, v108, v72
	v_fma_f32 v73, -v41, v109, v73
	v_fma_f32 v74, -v42, v110, v74
	v_fma_f32 v75, -v43, v111, v75
	ds_read_b128 v[40:43], v17 offset:8816
	v_fma_f32 v72, -v44, v112, v72
	v_fma_f32 v73, -v45, v113, v73
	v_fma_f32 v74, -v46, v114, v74
	v_fma_f32 v75, -v47, v115, v75
	ds_read_b128 v[44:47], v17 offset:8832
	s_waitcnt lgkmcnt(10)
	v_fma_f32 v72, -v48, v116, v72
	v_fma_f32 v73, -v49, v117, v73
	v_fma_f32 v74, -v50, v118, v74
	v_fma_f32 v75, -v51, v119, v75
	ds_read_b128 v[48:51], v17 offset:8960
	v_fma_f32 v72, -v52, v120, v72
	v_fma_f32 v73, -v53, v121, v73
	v_fma_f32 v74, -v54, v122, v74
	v_fma_f32 v75, -v55, v123, v75
	ds_read_b128 v[52:55], v17 offset:8976
	s_waitcnt lgkmcnt(10)
	v_fma_f32 v72, -v56, v124, v72
	ds_read_b128 v[56:59], v17 offset:8992
	v_add_f32_e32 v72, v72, v73
	v_add_f32_e32 v74, v74, v75
	v_add_f32_e32 v125, v125, v72
	v_add_f32_e32 v125, v125, v74
	v_mul_f32_e64 v72, -v4, v92
	v_mul_f32_e64 v73, -v5, v93
	v_mul_f32_e64 v74, -v6, v94
	v_mul_f32_e64 v75, -v7, v95
	ds_read_b128 v[4:7], v17 offset:9008
	s_waitcnt lgkmcnt(10)
	v_fma_f32 v72, -v8, v96, v72
	v_fma_f32 v73, -v9, v97, v73
	v_fma_f32 v74, -v10, v98, v74
	v_fma_f32 v75, -v11, v99, v75
	ds_read_b128 v[8:11], v17 offset:9024
	v_fma_f32 v72, -v12, v100, v72
	v_fma_f32 v73, -v13, v101, v73
	v_fma_f32 v74, -v14, v102, v74
	v_fma_f32 v75, -v15, v103, v75
	ds_read_b128 v[12:15], v17 offset:9040
	s_waitcnt lgkmcnt(10)
	v_fma_f32 v72, -v24, v104, v72
	v_fma_f32 v73, -v25, v105, v73
	v_fma_f32 v74, -v26, v106, v74
	v_fma_f32 v75, -v27, v107, v75
	ds_read_b128 v[24:27], v17 offset:9056
	v_fma_f32 v72, -v28, v108, v72
	v_fma_f32 v73, -v29, v109, v73
	v_fma_f32 v74, -v30, v110, v74
	v_fma_f32 v75, -v31, v111, v75
	ds_read_b128 v[28:31], v17 offset:9072
	s_waitcnt lgkmcnt(10)
	v_fma_f32 v72, -v32, v112, v72
	v_fma_f32 v73, -v33, v113, v73
	v_fma_f32 v74, -v34, v114, v74
	v_fma_f32 v75, -v35, v115, v75
	ds_read_b128 v[32:35], v17 offset:9088
	v_fma_f32 v72, -v36, v116, v72
	v_fma_f32 v73, -v37, v117, v73
	v_fma_f32 v74, -v38, v118, v74
	v_fma_f32 v75, -v39, v119, v75
	ds_read_b128 v[36:39], v17 offset:9216
	s_waitcnt lgkmcnt(10)
	v_fma_f32 v72, -v40, v120, v72
	v_fma_f32 v73, -v41, v121, v73
	v_fma_f32 v74, -v42, v122, v74
	v_fma_f32 v75, -v43, v123, v75
	ds_read_b128 v[40:43], v17 offset:9232
	v_fma_f32 v72, -v44, v124, v72
	v_fma_f32 v73, -v45, v125, v73
	ds_read_b128 v[44:47], v17 offset:9248
	v_add_f32_e32 v72, v72, v73
	v_add_f32_e32 v74, v74, v75
	v_add_f32_e32 v126, v126, v72
	v_add_f32_e32 v126, v126, v74
	s_waitcnt lgkmcnt(10)
; #define LAS __attribute__((address_space(3)))
; __device__ __forceinline__ void even_prep(const Ctx& c, const Params& p, int e) {
;     ...
;             for (int i = 1; i < 64; ++i) { const LAS f32x4* Lr = (const LAS f32x4*)(Lv + i * 64); float a0 = x[i], a1 = 0.f;
; #pragma unroll
;                 for (int j4 = 0; j4 < (i + 3) / 4; ++j4) { const f32x4 l = Lr[j4];
;                     if (4 * j4 + 0 < i) a0 -= l[0] * x[4 * j4 + 0];
;                     if (4 * j4 + 1 < i) a1 -= l[1] * x[4 * j4 + 1];
;                     if (4 * j4 + 2 < i) a0 -= l[2] * x[4 * j4 + 2];
;                     if (4 * j4 + 3 < i) a1 -= l[3] * x[4 * j4 + 3]; }
;                 x[i] = a0 + a1; }
	v_mul_f32_e64 v72, -v48, v92
	v_mul_f32_e64 v73, -v49, v93
	v_mul_f32_e64 v74, -v50, v94
	v_mul_f32_e64 v75, -v51, v95
	ds_read_b128 v[48:51], v17 offset:9264
	v_fma_f32 v72, -v52, v96, v72
	v_fma_f32 v73, -v53, v97, v73
	v_fma_f32 v74, -v54, v98, v74
	v_fma_f32 v75, -v55, v99, v75
	ds_read_b128 v[52:55], v17 offset:9280
	s_waitcnt lgkmcnt(10)
	v_fma_f32 v72, -v56, v100, v72
	v_fma_f32 v73, -v57, v101, v73
	v_fma_f32 v74, -v58, v102, v74
	v_fma_f32 v75, -v59, v103, v75
	ds_read_b128 v[56:59], v17 offset:9296
	v_fma_f32 v72, -v4, v104, v72
	v_fma_f32 v73, -v5, v105, v73
	v_fma_f32 v74, -v6, v106, v74
	v_fma_f32 v75, -v7, v107, v75
	ds_read_b128 v[4:7], v17 offset:9312
	s_waitcnt lgkmcnt(10)
	v_fma_f32 v72, -v8, v108, v72
	v_fma_f32 v73, -v9, v109, v73
	v_fma_f32 v74, -v10, v110, v74
	v_fma_f32 v75, -v11, v111, v75
	ds_read_b128 v[8:11], v17 offset:9328
	v_fma_f32 v72, -v12, v112, v72
	v_fma_f32 v73, -v13, v113, v73
	v_fma_f32 v74, -v14, v114, v74
	v_fma_f32 v75, -v15, v115, v75
	ds_read_b128 v[12:15], v17 offset:9344
	s_waitcnt lgkmcnt(10)
	v_fma_f32 v72, -v24, v116, v72
	v_fma_f32 v73, -v25, v117, v73
	v_fma_f32 v74, -v26, v118, v74
	v_fma_f32 v75, -v27, v119, v75
	ds_read_b128 v[24:27], v17 offset:9472
	v_fma_f32 v72, -v28, v120, v72
	v_fma_f32 v73, -v29, v121, v73
	v_fma_f32 v74, -v30, v122, v74
	v_fma_f32 v75, -v31, v123, v75
	ds_read_b128 v[28:31], v17 offset:9488
	s_waitcnt lgkmcnt(10)
	v_fma_f32 v72, -v32, v124, v72
	v_fma_f32 v73, -v33, v125, v73
	v_fma_f32 v74, -v34, v126, v74
	ds_read_b128 v[32:35], v17 offset:9504
	v_add_f32_e32 v72, v72, v73
	v_add_f32_e32 v74, v74, v75
	v_add_f32_e32 v127, v127, v72
	v_add_f32_e32 v127, v127, v74
	v_mul_f32_e64 v72, -v36, v92
	v_mul_f32_e64 v73, -v37, v93
	v_mul_f32_e64 v74, -v38, v94
	v_mul_f32_e64 v75, -v39, v95
	ds_read_b128 v[36:39], v17 offset:9520
	s_waitcnt lgkmcnt(10)
	v_fma_f32 v72, -v40, v96, v72
	v_fma_f32 v73, -v41, v97, v73
	v_fma_f32 v74, -v42, v98, v74
	v_fma_f32 v75, -v43, v99, v75
	ds_read_b128 v[40:43], v17 offset:9536
	v_fma_f32 v72, -v44, v100, v72
	v_fma_f32 v73, -v45, v101, v73
	v_fma_f32 v74, -v46, v102, v74
	v_fma_f32 v75, -v47, v103, v75
	ds_read_b128 v[44:47], v17 offset:9552
	s_waitcnt lgkmcnt(10)
	v_fma_f32 v72, -v48, v104, v72
	v_fma_f32 v73, -v49, v105, v73
	v_fma_f32 v74, -v50, v106, v74
	v_fma_f32 v75, -v51, v107, v75
	ds_read_b128 v[48:51], v17 offset:9568
	v_fma_f32 v72, -v52, v108, v72
	v_fma_f32 v73, -v53, v109, v73
	v_fma_f32 v74, -v54, v110, v74
	v_fma_f32 v75, -v55, v111, v75
	ds_read_b128 v[52:55], v17 offset:9584
	s_waitcnt lgkmcnt(10)
	v_fma_f32 v72, -v56, v112, v72
	v_fma_f32 v73, -v57, v113, v73
	v_fma_f32 v74, -v58, v114, v74
	v_fma_f32 v75, -v59, v115, v75
	ds_read_b128 v[56:59], v17 offset:9600
	v_fma_f32 v72, -v4, v116, v72
	v_fma_f32 v73, -v5, v117, v73
	v_fma_f32 v74, -v6, v118, v74
	v_fma_f32 v75, -v7, v119, v75
	ds_read_b128 v[4:7], v17 offset:9616
	s_waitcnt lgkmcnt(10)
	v_fma_f32 v72, -v8, v120, v72
	v_fma_f32 v73, -v9, v121, v73
	v_fma_f32 v74, -v10, v122, v74
	v_fma_f32 v75, -v11, v123, v75
	ds_read_b128 v[8:11], v17 offset:9728
	v_fma_f32 v72, -v12, v124, v72
	v_fma_f32 v73, -v13, v125, v73
	v_fma_f32 v74, -v14, v126, v74
	v_fma_f32 v75, -v15, v127, v75
	ds_read_b128 v[12:15], v17 offset:9744
	v_add_f32_e32 v72, v72, v73
	v_add_f32_e32 v74, v74, v75
	v_add_f32_e32 v128, v128, v72
	v_add_f32_e32 v128, v128, v74
	s_waitcnt lgkmcnt(10)
	v_mul_f32_e64 v72, -v24, v92
	v_mul_f32_e64 v73, -v25, v93
	v_mul_f32_e64 v74, -v26, v94
	v_mul_f32_e64 v75, -v27, v95
	ds_read_b128 v[24:27], v17 offset:9760
	v_fma_f32 v72, -v28, v96, v72
	v_fma_f32 v73, -v29, v97, v73
	v_fma_f32 v74, -v30, v98, v74
	v_fma_f32 v75, -v31, v99, v75
	ds_read_b128 v[28:31], v17 offset:9776
	s_waitcnt lgkmcnt(10)
	v_fma_f32 v72, -v32, v100, v72
	v_fma_f32 v73, -v33, v101, v73
	v_fma_f32 v74, -v34, v102, v74
	v_fma_f32 v75, -v35, v103, v75
	ds_read_b128 v[32:35], v17 offset:9792
	v_fma_f32 v72, -v36, v104, v72
	v_fma_f32 v73, -v37, v105, v73
	v_fma_f32 v74, -v38, v106, v74
	v_fma_f32 v75, -v39, v107, v75
	ds_read_b128 v[36:39], v17 offset:9808
	s_waitcnt lgkmcnt(10)
	v_fma_f32 v72, -v40, v108, v72
	v_fma_f32 v73, -v41, v109, v73
	v_fma_f32 v74, -v42, v110, v74
	v_fma_f32 v75, -v43, v111, v75
	ds_read_b128 v[40:43], v17 offset:9824
	v_fma_f32 v72, -v44, v112, v72
	v_fma_f32 v73, -v45, v113, v73
	v_fma_f32 v74, -v46, v114, v74
	v_fma_f32 v75, -v47, v115, v75
	ds_read_b128 v[44:47], v17 offset:9840
	s_waitcnt lgkmcnt(10)
	v_fma_f32 v72, -v48, v116, v72
	v_fma_f32 v73, -v49, v117, v73
	v_fma_f32 v74, -v50, v118, v74
	v_fma_f32 v75, -v51, v119, v75
	ds_read_b128 v[48:51], v17 offset:9856
	v_fma_f32 v72, -v52, v120, v72
	v_fma_f32 v73, -v53, v121, v73
	v_fma_f32 v74, -v54, v122, v74
	v_fma_f32 v75, -v55, v123, v75
	ds_read_b128 v[52:55], v17 offset:9872
	s_waitcnt lgkmcnt(10)
	v_fma_f32 v72, -v56, v124, v72
	v_fma_f32 v73, -v57, v125, v73
	v_fma_f32 v74, -v58, v126, v74
	v_fma_f32 v75, -v59, v127, v75
	ds_read_b128 v[56:59], v17 offset:9984
	v_fma_f32 v72, -v4, v128, v72
	ds_read_b128 v[4:7], v17 offset:10000
	v_add_f32_e32 v72, v72, v73
	v_add_f32_e32 v74, v74, v75
	v_add_f32_e32 v129, v129, v72
	v_add_f32_e32 v129, v129, v74
	s_waitcnt lgkmcnt(10)
	v_mul_f32_e64 v72, -v8, v92
	v_mul_f32_e64 v73, -v9, v93
	v_mul_f32_e64 v74, -v10, v94
	v_mul_f32_e64 v75, -v11, v95
	ds_read_b128 v[8:11], v17 offset:10016
	v_fma_f32 v72, -v12, v96, v72
	v_fma_f32 v73, -v13, v97, v73
	v_fma_f32 v74, -v14, v98, v74
	v_fma_f32 v75, -v15, v99, v75
	ds_read_b128 v[12:15], v17 offset:10032
	s_waitcnt lgkmcnt(10)
; #define LAS __attribute__((address_space(3)))
; __device__ __forceinline__ void even_prep(const Ctx& c, const Params& p, int e) {
;     ...
;             for (int i = 1; i < 64; ++i) { const LAS f32x4* Lr = (const LAS f32x4*)(Lv + i * 64); float a0 = x[i], a1 = 0.f;
; #pragma unroll
;                 for (int j4 = 0; j4 < (i + 3) / 4; ++j4) { const f32x4 l = Lr[j4];
;                     if (4 * j4 + 0 < i) a0 -= l[0] * x[4 * j4 + 0];
;                     if (4 * j4 + 1 < i) a1 -= l[1] * x[4 * j4 + 1];
;                     if (4 * j4 + 2 < i) a0 -= l[2] * x[4 * j4 + 2];
;                     if (4 * j4 + 3 < i) a1 -= l[3] * x[4 * j4 + 3]; }
;                 x[i] = a0 + a1; }
	v_fma_f32 v72, -v24, v100, v72
	v_fma_f32 v73, -v25, v101, v73
	v_fma_f32 v74, -v26, v102, v74
	v_fma_f32 v75, -v27, v103, v75
	ds_read_b128 v[24:27], v17 offset:10048
	v_fma_f32 v72, -v28, v104, v72
	v_fma_f32 v73, -v29, v105, v73
	v_fma_f32 v74, -v30, v106, v74
	v_fma_f32 v75, -v31, v107, v75
	ds_read_b128 v[28:31], v17 offset:10064
	s_waitcnt lgkmcnt(10)
	v_fma_f32 v72, -v32, v108, v72
	v_fma_f32 v73, -v33, v109, v73
	v_fma_f32 v74, -v34, v110, v74
	v_fma_f32 v75, -v35, v111, v75
	ds_read_b128 v[32:35], v17 offset:10080
	v_fma_f32 v72, -v36, v112, v72
	v_fma_f32 v73, -v37, v113, v73
	v_fma_f32 v74, -v38, v114, v74
	v_fma_f32 v75, -v39, v115, v75
	ds_read_b128 v[36:39], v17 offset:10096
	s_waitcnt lgkmcnt(10)
	v_fma_f32 v72, -v40, v116, v72
	v_fma_f32 v73, -v41, v117, v73
	v_fma_f32 v74, -v42, v118, v74
	v_fma_f32 v75, -v43, v119, v75
	ds_read_b128 v[40:43], v17 offset:10112
	v_fma_f32 v72, -v44, v120, v72
	v_fma_f32 v73, -v45, v121, v73
	v_fma_f32 v74, -v46, v122, v74
	v_fma_f32 v75, -v47, v123, v75
	ds_read_b128 v[44:47], v17 offset:10128
	s_waitcnt lgkmcnt(10)
	v_fma_f32 v72, -v48, v124, v72
	v_fma_f32 v73, -v49, v125, v73
	v_fma_f32 v74, -v50, v126, v74
	v_fma_f32 v75, -v51, v127, v75
	ds_read_b128 v[48:51], v17 offset:10240
	v_fma_f32 v72, -v52, v128, v72
	v_fma_f32 v73, -v53, v129, v73
	ds_read_b128 v[52:55], v17 offset:10256
	v_add_f32_e32 v72, v72, v73
	v_add_f32_e32 v74, v74, v75
	v_add_f32_e32 v130, v130, v72
	v_add_f32_e32 v130, v130, v74
	s_waitcnt lgkmcnt(10)
	v_mul_f32_e64 v72, -v56, v92
	v_mul_f32_e64 v73, -v57, v93
	v_mul_f32_e64 v74, -v58, v94
	v_mul_f32_e64 v75, -v59, v95
	ds_read_b128 v[56:59], v17 offset:10272
	v_fma_f32 v72, -v4, v96, v72
	v_fma_f32 v73, -v5, v97, v73
	v_fma_f32 v74, -v6, v98, v74
	v_fma_f32 v75, -v7, v99, v75
	ds_read_b128 v[4:7], v17 offset:10288
	s_waitcnt lgkmcnt(10)
	v_fma_f32 v72, -v8, v100, v72
	v_fma_f32 v73, -v9, v101, v73
	v_fma_f32 v74, -v10, v102, v74
	v_fma_f32 v75, -v11, v103, v75
	ds_read_b128 v[8:11], v17 offset:10304
	v_fma_f32 v72, -v12, v104, v72
	v_fma_f32 v73, -v13, v105, v73
	v_fma_f32 v74, -v14, v106, v74
	v_fma_f32 v75, -v15, v107, v75
	ds_read_b128 v[12:15], v17 offset:10320
	s_waitcnt lgkmcnt(10)
	v_fma_f32 v72, -v24, v108, v72
	v_fma_f32 v73, -v25, v109, v73
	v_fma_f32 v74, -v26, v110, v74
	v_fma_f32 v75, -v27, v111, v75
	ds_read_b128 v[24:27], v17 offset:10336
	v_fma_f32 v72, -v28, v112, v72
	v_fma_f32 v73, -v29, v113, v73
	v_fma_f32 v74, -v30, v114, v74
	v_fma_f32 v75, -v31, v115, v75
	ds_read_b128 v[28:31], v17 offset:10352
	s_waitcnt lgkmcnt(10)
	v_fma_f32 v72, -v32, v116, v72
	v_fma_f32 v73, -v33, v117, v73
	v_fma_f32 v74, -v34, v118, v74
	v_fma_f32 v75, -v35, v119, v75
	ds_read_b128 v[32:35], v17 offset:10368
	v_fma_f32 v72, -v36, v120, v72
	v_fma_f32 v73, -v37, v121, v73
	v_fma_f32 v74, -v38, v122, v74
	v_fma_f32 v75, -v39, v123, v75
	ds_read_b128 v[36:39], v17 offset:10384
	s_waitcnt lgkmcnt(10)
	v_fma_f32 v72, -v40, v124, v72
	v_fma_f32 v73, -v41, v125, v73
	v_fma_f32 v74, -v42, v126, v74
	v_fma_f32 v75, -v43, v127, v75
	ds_read_b128 v[40:43], v17 offset:10496
	v_fma_f32 v72, -v44, v128, v72
	v_fma_f32 v73, -v45, v129, v73
	v_fma_f32 v74, -v46, v130, v74
	ds_read_b128 v[44:47], v17 offset:10512
	v_add_f32_e32 v72, v72, v73
	v_add_f32_e32 v74, v74, v75
	v_add_f32_e32 v131, v131, v72
	v_add_f32_e32 v131, v131, v74
	s_waitcnt lgkmcnt(10)
	v_mul_f32_e64 v72, -v48, v92
	v_mul_f32_e64 v73, -v49, v93
	v_mul_f32_e64 v74, -v50, v94
	v_mul_f32_e64 v75, -v51, v95
	ds_read_b128 v[48:51], v17 offset:10528
	v_fma_f32 v72, -v52, v96, v72
	v_fma_f32 v73, -v53, v97, v73
	v_fma_f32 v74, -v54, v98, v74
	v_fma_f32 v75, -v55, v99, v75
	ds_read_b128 v[52:55], v17 offset:10544
	s_waitcnt lgkmcnt(10)
	v_fma_f32 v72, -v56, v100, v72
	v_fma_f32 v73, -v57, v101, v73
	v_fma_f32 v74, -v58, v102, v74
	v_fma_f32 v75, -v59, v103, v75
	ds_read_b128 v[56:59], v17 offset:10560
	v_fma_f32 v72, -v4, v104, v72
	v_fma_f32 v73, -v5, v105, v73
	v_fma_f32 v74, -v6, v106, v74
	v_fma_f32 v75, -v7, v107, v75
	ds_read_b128 v[4:7], v17 offset:10576
	s_waitcnt lgkmcnt(10)
	v_fma_f32 v72, -v8, v108, v72
	v_fma_f32 v73, -v9, v109, v73
	v_fma_f32 v74, -v10, v110, v74
	v_fma_f32 v75, -v11, v111, v75
	ds_read_b128 v[8:11], v17 offset:10592
	v_fma_f32 v72, -v12, v112, v72
	v_fma_f32 v73, -v13, v113, v73
	v_fma_f32 v74, -v14, v114, v74
	v_fma_f32 v75, -v15, v115, v75
	ds_read_b128 v[12:15], v17 offset:10608
	s_waitcnt lgkmcnt(10)
	v_fma_f32 v72, -v24, v116, v72
	v_fma_f32 v73, -v25, v117, v73
	v_fma_f32 v74, -v26, v118, v74
	v_fma_f32 v75, -v27, v119, v75
	ds_read_b128 v[24:27], v17 offset:10624
	v_fma_f32 v72, -v28, v120, v72
	v_fma_f32 v73, -v29, v121, v73
	v_fma_f32 v74, -v30, v122, v74
	v_fma_f32 v75, -v31, v123, v75
	ds_read_b128 v[28:31], v17 offset:10640
	s_waitcnt lgkmcnt(10)
	v_fma_f32 v72, -v32, v124, v72
	v_fma_f32 v73, -v33, v125, v73
	v_fma_f32 v74, -v34, v126, v74
	v_fma_f32 v75, -v35, v127, v75
	ds_read_b128 v[32:35], v17 offset:10656
	v_fma_f32 v72, -v36, v128, v72
	v_fma_f32 v73, -v37, v129, v73
	v_fma_f32 v74, -v38, v130, v74
	v_fma_f32 v75, -v39, v131, v75
	ds_read_b128 v[36:39], v17 offset:10752
	v_add_f32_e32 v72, v72, v73
	v_add_f32_e32 v74, v74, v75
	v_add_f32_e32 v132, v132, v72
	v_add_f32_e32 v132, v132, v74
	s_waitcnt lgkmcnt(10)
	v_mul_f32_e64 v72, -v40, v92
	v_mul_f32_e64 v73, -v41, v93
	v_mul_f32_e64 v74, -v42, v94
	v_mul_f32_e64 v75, -v43, v95
	ds_read_b128 v[40:43], v17 offset:10768
	v_fma_f32 v72, -v44, v96, v72
	v_fma_f32 v73, -v45, v97, v73
	v_fma_f32 v74, -v46, v98, v74
	v_fma_f32 v75, -v47, v99, v75
	ds_read_b128 v[44:47], v17 offset:10784
	s_waitcnt lgkmcnt(10)
; #define LAS __attribute__((address_space(3)))
; __device__ __forceinline__ void even_prep(const Ctx& c, const Params& p, int e) {
;     ...
;             for (int i = 1; i < 64; ++i) { const LAS f32x4* Lr = (const LAS f32x4*)(Lv + i * 64); float a0 = x[i], a1 = 0.f;
; #pragma unroll
;                 for (int j4 = 0; j4 < (i + 3) / 4; ++j4) { const f32x4 l = Lr[j4];
;                     if (4 * j4 + 0 < i) a0 -= l[0] * x[4 * j4 + 0];
;                     if (4 * j4 + 1 < i) a1 -= l[1] * x[4 * j4 + 1];
;                     if (4 * j4 + 2 < i) a0 -= l[2] * x[4 * j4 + 2];
;                     if (4 * j4 + 3 < i) a1 -= l[3] * x[4 * j4 + 3]; }
;                 x[i] = a0 + a1; }
	v_fma_f32 v72, -v48, v100, v72
	v_fma_f32 v73, -v49, v101, v73
	v_fma_f32 v74, -v50, v102, v74
	v_fma_f32 v75, -v51, v103, v75
	ds_read_b128 v[48:51], v17 offset:10800
	v_fma_f32 v72, -v52, v104, v72
	v_fma_f32 v73, -v53, v105, v73
	v_fma_f32 v74, -v54, v106, v74
	v_fma_f32 v75, -v55, v107, v75
	ds_read_b128 v[52:55], v17 offset:10816
	s_waitcnt lgkmcnt(10)
	v_fma_f32 v72, -v56, v108, v72
	v_fma_f32 v73, -v57, v109, v73
	v_fma_f32 v74, -v58, v110, v74
	v_fma_f32 v75, -v59, v111, v75
	ds_read_b128 v[56:59], v17 offset:10832
	v_fma_f32 v72, -v4, v112, v72
	v_fma_f32 v73, -v5, v113, v73
	v_fma_f32 v74, -v6, v114, v74
	v_fma_f32 v75, -v7, v115, v75
	ds_read_b128 v[4:7], v17 offset:10848
	s_waitcnt lgkmcnt(10)
	v_fma_f32 v72, -v8, v116, v72
	v_fma_f32 v73, -v9, v117, v73
	v_fma_f32 v74, -v10, v118, v74
	v_fma_f32 v75, -v11, v119, v75
	ds_read_b128 v[8:11], v17 offset:10864
	v_fma_f32 v72, -v12, v120, v72
	v_fma_f32 v73, -v13, v121, v73
	v_fma_f32 v74, -v14, v122, v74
	v_fma_f32 v75, -v15, v123, v75
	ds_read_b128 v[12:15], v17 offset:10880
	s_waitcnt lgkmcnt(10)
	v_fma_f32 v72, -v24, v124, v72
	v_fma_f32 v73, -v25, v125, v73
	v_fma_f32 v74, -v26, v126, v74
	v_fma_f32 v75, -v27, v127, v75
	ds_read_b128 v[24:27], v17 offset:10896
	v_fma_f32 v72, -v28, v128, v72
	v_fma_f32 v73, -v29, v129, v73
	v_fma_f32 v74, -v30, v130, v74
	v_fma_f32 v75, -v31, v131, v75
	ds_read_b128 v[28:31], v17 offset:10912
	s_waitcnt lgkmcnt(10)
	v_fma_f32 v72, -v32, v132, v72
	ds_read_b128 v[32:35], v17 offset:11008
	v_add_f32_e32 v72, v72, v73
	v_add_f32_e32 v74, v74, v75
	v_add_f32_e32 v133, v133, v72
	v_add_f32_e32 v133, v133, v74
	v_mul_f32_e64 v72, -v36, v92
	v_mul_f32_e64 v73, -v37, v93
	v_mul_f32_e64 v74, -v38, v94
	v_mul_f32_e64 v75, -v39, v95
	ds_read_b128 v[36:39], v17 offset:11024
	s_waitcnt lgkmcnt(10)
	v_fma_f32 v72, -v40, v96, v72
	v_fma_f32 v73, -v41, v97, v73
	v_fma_f32 v74, -v42, v98, v74
	v_fma_f32 v75, -v43, v99, v75
	ds_read_b128 v[40:43], v17 offset:11040
	v_fma_f32 v72, -v44, v100, v72
	v_fma_f32 v73, -v45, v101, v73
	v_fma_f32 v74, -v46, v102, v74
	v_fma_f32 v75, -v47, v103, v75
	ds_read_b128 v[44:47], v17 offset:11056
	s_waitcnt lgkmcnt(10)
	v_fma_f32 v72, -v48, v104, v72
	v_fma_f32 v73, -v49, v105, v73
	v_fma_f32 v74, -v50, v106, v74
	v_fma_f32 v75, -v51, v107, v75
	ds_read_b128 v[48:51], v17 offset:11072
	v_fma_f32 v72, -v52, v108, v72
	v_fma_f32 v73, -v53, v109, v73
	v_fma_f32 v74, -v54, v110, v74
	v_fma_f32 v75, -v55, v111, v75
	ds_read_b128 v[52:55], v17 offset:11088
	s_waitcnt lgkmcnt(10)
	v_fma_f32 v72, -v56, v112, v72
	v_fma_f32 v73, -v57, v113, v73
	v_fma_f32 v74, -v58, v114, v74
	v_fma_f32 v75, -v59, v115, v75
	ds_read_b128 v[56:59], v17 offset:11104
	v_fma_f32 v72, -v4, v116, v72
	v_fma_f32 v73, -v5, v117, v73
	v_fma_f32 v74, -v6, v118, v74
	v_fma_f32 v75, -v7, v119, v75
	ds_read_b128 v[4:7], v17 offset:11120
	s_waitcnt lgkmcnt(10)
	v_fma_f32 v72, -v8, v120, v72
	v_fma_f32 v73, -v9, v121, v73
	v_fma_f32 v74, -v10, v122, v74
	v_fma_f32 v75, -v11, v123, v75
	ds_read_b128 v[8:11], v17 offset:11136
	v_fma_f32 v72, -v12, v124, v72
	v_fma_f32 v73, -v13, v125, v73
	v_fma_f32 v74, -v14, v126, v74
	v_fma_f32 v75, -v15, v127, v75
	ds_read_b128 v[12:15], v17 offset:11152
	s_waitcnt lgkmcnt(10)
	v_fma_f32 v72, -v24, v128, v72
	v_fma_f32 v73, -v25, v129, v73
	v_fma_f32 v74, -v26, v130, v74
	v_fma_f32 v75, -v27, v131, v75
	ds_read_b128 v[24:27], v17 offset:11168
	v_fma_f32 v72, -v28, v132, v72
	v_fma_f32 v73, -v29, v133, v73
	ds_read_b128 v[28:31], v17 offset:11264
	v_add_f32_e32 v72, v72, v73
	v_add_f32_e32 v74, v74, v75
	v_add_f32_e32 v134, v134, v72
	v_add_f32_e32 v134, v134, v74
	s_waitcnt lgkmcnt(10)
	v_mul_f32_e64 v72, -v32, v92
	v_mul_f32_e64 v73, -v33, v93
	v_mul_f32_e64 v74, -v34, v94
	v_mul_f32_e64 v75, -v35, v95
	ds_read_b128 v[32:35], v17 offset:11280
	v_fma_f32 v72, -v36, v96, v72
	v_fma_f32 v73, -v37, v97, v73
	v_fma_f32 v74, -v38, v98, v74
	v_fma_f32 v75, -v39, v99, v75
	ds_read_b128 v[36:39], v17 offset:11296
	s_waitcnt lgkmcnt(10)
	v_fma_f32 v72, -v40, v100, v72
	v_fma_f32 v73, -v41, v101, v73
	v_fma_f32 v74, -v42, v102, v74
	v_fma_f32 v75, -v43, v103, v75
	ds_read_b128 v[40:43], v17 offset:11312
	v_fma_f32 v72, -v44, v104, v72
	v_fma_f32 v73, -v45, v105, v73
	v_fma_f32 v74, -v46, v106, v74
	v_fma_f32 v75, -v47, v107, v75
	ds_read_b128 v[44:47], v17 offset:11328
	s_waitcnt lgkmcnt(10)
	v_fma_f32 v72, -v48, v108, v72
	v_fma_f32 v73, -v49, v109, v73
	v_fma_f32 v74, -v50, v110, v74
	v_fma_f32 v75, -v51, v111, v75
	ds_read_b128 v[48:51], v17 offset:11344
	v_fma_f32 v72, -v52, v112, v72
	v_fma_f32 v73, -v53, v113, v73
	v_fma_f32 v74, -v54, v114, v74
	v_fma_f32 v75, -v55, v115, v75
	ds_read_b128 v[52:55], v17 offset:11360
	s_waitcnt lgkmcnt(10)
	v_fma_f32 v72, -v56, v116, v72
	v_fma_f32 v73, -v57, v117, v73
	v_fma_f32 v74, -v58, v118, v74
	v_fma_f32 v75, -v59, v119, v75
	ds_read_b128 v[56:59], v17 offset:11376
	v_fma_f32 v72, -v4, v120, v72
	v_fma_f32 v73, -v5, v121, v73
	v_fma_f32 v74, -v6, v122, v74
	v_fma_f32 v75, -v7, v123, v75
	ds_read_b128 v[4:7], v17 offset:11392
	s_waitcnt lgkmcnt(10)
	v_fma_f32 v72, -v8, v124, v72
	v_fma_f32 v73, -v9, v125, v73
	v_fma_f32 v74, -v10, v126, v74
	v_fma_f32 v75, -v11, v127, v75
	ds_read_b128 v[8:11], v17 offset:11408
	v_fma_f32 v72, -v12, v128, v72
	v_fma_f32 v73, -v13, v129, v73
	v_fma_f32 v74, -v14, v130, v74
	v_fma_f32 v75, -v15, v131, v75
	ds_read_b128 v[12:15], v17 offset:11424
	s_waitcnt lgkmcnt(10)
; #define LAS __attribute__((address_space(3)))
; __device__ __forceinline__ void even_prep(const Ctx& c, const Params& p, int e) {
;     ...
;             for (int i = 1; i < 64; ++i) { const LAS f32x4* Lr = (const LAS f32x4*)(Lv + i * 64); float a0 = x[i], a1 = 0.f;
; #pragma unroll
;                 for (int j4 = 0; j4 < (i + 3) / 4; ++j4) { const f32x4 l = Lr[j4];
;                     if (4 * j4 + 0 < i) a0 -= l[0] * x[4 * j4 + 0];
;                     if (4 * j4 + 1 < i) a1 -= l[1] * x[4 * j4 + 1];
;                     if (4 * j4 + 2 < i) a0 -= l[2] * x[4 * j4 + 2];
;                     if (4 * j4 + 3 < i) a1 -= l[3] * x[4 * j4 + 3]; }
;                 x[i] = a0 + a1; }
	v_fma_f32 v72, -v24, v132, v72
	v_fma_f32 v73, -v25, v133, v73
	v_fma_f32 v74, -v26, v134, v74
	ds_read_b128 v[24:27], v17 offset:11520
	v_add_f32_e32 v72, v72, v73
	v_add_f32_e32 v74, v74, v75
	v_add_f32_e32 v135, v135, v72
	v_add_f32_e32 v135, v135, v74
	v_mul_f32_e64 v72, -v28, v92
	v_mul_f32_e64 v73, -v29, v93
	v_mul_f32_e64 v74, -v30, v94
	v_mul_f32_e64 v75, -v31, v95
	ds_read_b128 v[28:31], v17 offset:11536
	s_waitcnt lgkmcnt(10)
	v_fma_f32 v72, -v32, v96, v72
	v_fma_f32 v73, -v33, v97, v73
	v_fma_f32 v74, -v34, v98, v74
	v_fma_f32 v75, -v35, v99, v75
	ds_read_b128 v[32:35], v17 offset:11552
	v_fma_f32 v72, -v36, v100, v72
	v_fma_f32 v73, -v37, v101, v73
	v_fma_f32 v74, -v38, v102, v74
	v_fma_f32 v75, -v39, v103, v75
	ds_read_b128 v[36:39], v17 offset:11568
	s_waitcnt lgkmcnt(10)
	v_fma_f32 v72, -v40, v104, v72
	v_fma_f32 v73, -v41, v105, v73
	v_fma_f32 v74, -v42, v106, v74
	v_fma_f32 v75, -v43, v107, v75
	ds_read_b128 v[40:43], v17 offset:11584
	v_fma_f32 v72, -v44, v108, v72
	v_fma_f32 v73, -v45, v109, v73
	v_fma_f32 v74, -v46, v110, v74
	v_fma_f32 v75, -v47, v111, v75
	ds_read_b128 v[44:47], v17 offset:11600
	s_waitcnt lgkmcnt(10)
	v_fma_f32 v72, -v48, v112, v72
	v_fma_f32 v73, -v49, v113, v73
	v_fma_f32 v74, -v50, v114, v74
	v_fma_f32 v75, -v51, v115, v75
	ds_read_b128 v[48:51], v17 offset:11616
	v_fma_f32 v72, -v52, v116, v72
	v_fma_f32 v73, -v53, v117, v73
	v_fma_f32 v74, -v54, v118, v74
	v_fma_f32 v75, -v55, v119, v75
	ds_read_b128 v[52:55], v17 offset:11632
	s_waitcnt lgkmcnt(10)
	v_fma_f32 v72, -v56, v120, v72
	v_fma_f32 v73, -v57, v121, v73
	v_fma_f32 v74, -v58, v122, v74
	v_fma_f32 v75, -v59, v123, v75
	ds_read_b128 v[56:59], v17 offset:11648
	v_fma_f32 v72, -v4, v124, v72
	v_fma_f32 v73, -v5, v125, v73
	v_fma_f32 v74, -v6, v126, v74
	v_fma_f32 v75, -v7, v127, v75
	ds_read_b128 v[4:7], v17 offset:11664
	s_waitcnt lgkmcnt(10)
	v_fma_f32 v72, -v8, v128, v72
	v_fma_f32 v73, -v9, v129, v73
	v_fma_f32 v74, -v10, v130, v74
	v_fma_f32 v75, -v11, v131, v75
	ds_read_b128 v[8:11], v17 offset:11680
	v_fma_f32 v72, -v12, v132, v72
	v_fma_f32 v73, -v13, v133, v73
	v_fma_f32 v74, -v14, v134, v74
	v_fma_f32 v75, -v15, v135, v75
	ds_read_b128 v[12:15], v17 offset:11696
	v_add_f32_e32 v72, v72, v73
	v_add_f32_e32 v74, v74, v75
	v_add_f32_e32 v136, v136, v72
	v_add_f32_e32 v136, v136, v74
	s_waitcnt lgkmcnt(10)
	v_mul_f32_e64 v72, -v24, v92
	v_mul_f32_e64 v73, -v25, v93
	v_mul_f32_e64 v74, -v26, v94
	v_mul_f32_e64 v75, -v27, v95
	ds_read_b128 v[24:27], v17 offset:11776
	v_fma_f32 v72, -v28, v96, v72
	v_fma_f32 v73, -v29, v97, v73
	v_fma_f32 v74, -v30, v98, v74
	v_fma_f32 v75, -v31, v99, v75
	ds_read_b128 v[28:31], v17 offset:11792
	s_waitcnt lgkmcnt(10)
	v_fma_f32 v72, -v32, v100, v72
	v_fma_f32 v73, -v33, v101, v73
	v_fma_f32 v74, -v34, v102, v74
	v_fma_f32 v75, -v35, v103, v75
	ds_read_b128 v[32:35], v17 offset:11808
	v_fma_f32 v72, -v36, v104, v72
	v_fma_f32 v73, -v37, v105, v73
	v_fma_f32 v74, -v38, v106, v74
	v_fma_f32 v75, -v39, v107, v75
	ds_read_b128 v[36:39], v17 offset:11824
	s_waitcnt lgkmcnt(10)
	v_fma_f32 v72, -v40, v108, v72
	v_fma_f32 v73, -v41, v109, v73
	v_fma_f32 v74, -v42, v110, v74
	v_fma_f32 v75, -v43, v111, v75
	ds_read_b128 v[40:43], v17 offset:11840
	v_fma_f32 v72, -v44, v112, v72
	v_fma_f32 v73, -v45, v113, v73
	v_fma_f32 v74, -v46, v114, v74
	v_fma_f32 v75, -v47, v115, v75
	ds_read_b128 v[44:47], v17 offset:11856
	s_waitcnt lgkmcnt(10)
	v_fma_f32 v72, -v48, v116, v72
	v_fma_f32 v73, -v49, v117, v73
	v_fma_f32 v74, -v50, v118, v74
	v_fma_f32 v75, -v51, v119, v75
	ds_read_b128 v[48:51], v17 offset:11872
	v_fma_f32 v72, -v52, v120, v72
	v_fma_f32 v73, -v53, v121, v73
	v_fma_f32 v74, -v54, v122, v74
	v_fma_f32 v75, -v55, v123, v75
	ds_read_b128 v[52:55], v17 offset:11888
	s_waitcnt lgkmcnt(10)
	v_fma_f32 v72, -v56, v124, v72
	v_fma_f32 v73, -v57, v125, v73
	v_fma_f32 v74, -v58, v126, v74
	v_fma_f32 v75, -v59, v127, v75
	ds_read_b128 v[56:59], v17 offset:11904
	v_fma_f32 v72, -v4, v128, v72
	v_fma_f32 v73, -v5, v129, v73
	v_fma_f32 v74, -v6, v130, v74
	v_fma_f32 v75, -v7, v131, v75
	ds_read_b128 v[4:7], v17 offset:11920
	s_waitcnt lgkmcnt(10)
	v_fma_f32 v72, -v8, v132, v72
	v_fma_f32 v73, -v9, v133, v73
	v_fma_f32 v74, -v10, v134, v74
	v_fma_f32 v75, -v11, v135, v75
	ds_read_b128 v[8:11], v17 offset:11936
	v_fma_f32 v72, -v12, v136, v72
	ds_read_b128 v[12:15], v17 offset:11952
	v_add_f32_e32 v72, v72, v73
	v_add_f32_e32 v74, v74, v75
	v_add_f32_e32 v137, v137, v72
	v_add_f32_e32 v137, v137, v74
	s_waitcnt lgkmcnt(10)
	v_mul_f32_e64 v72, -v24, v92
	v_mul_f32_e64 v73, -v25, v93
	v_mul_f32_e64 v74, -v26, v94
	v_mul_f32_e64 v75, -v27, v95
	ds_read_b128 v[24:27], v17 offset:12032
	v_fma_f32 v72, -v28, v96, v72
	v_fma_f32 v73, -v29, v97, v73
	v_fma_f32 v74, -v30, v98, v74
	v_fma_f32 v75, -v31, v99, v75
	ds_read_b128 v[28:31], v17 offset:12048
	s_waitcnt lgkmcnt(10)
	v_fma_f32 v72, -v32, v100, v72
	v_fma_f32 v73, -v33, v101, v73
	v_fma_f32 v74, -v34, v102, v74
	v_fma_f32 v75, -v35, v103, v75
	ds_read_b128 v[32:35], v17 offset:12064
	v_fma_f32 v72, -v36, v104, v72
	v_fma_f32 v73, -v37, v105, v73
	v_fma_f32 v74, -v38, v106, v74
	v_fma_f32 v75, -v39, v107, v75
	ds_read_b128 v[36:39], v17 offset:12080
	s_waitcnt lgkmcnt(10)
	v_fma_f32 v72, -v40, v108, v72
	v_fma_f32 v73, -v41, v109, v73
	v_fma_f32 v74, -v42, v110, v74
	v_fma_f32 v75, -v43, v111, v75
	ds_read_b128 v[40:43], v17 offset:12096
	v_fma_f32 v72, -v44, v112, v72
	v_fma_f32 v73, -v45, v113, v73
	v_fma_f32 v74, -v46, v114, v74
	v_fma_f32 v75, -v47, v115, v75
	ds_read_b128 v[44:47], v17 offset:12112
	s_waitcnt lgkmcnt(10)
; #define LAS __attribute__((address_space(3)))
; __device__ __forceinline__ void even_prep(const Ctx& c, const Params& p, int e) {
;     ...
;             for (int i = 1; i < 64; ++i) { const LAS f32x4* Lr = (const LAS f32x4*)(Lv + i * 64); float a0 = x[i], a1 = 0.f;
; #pragma unroll
;                 for (int j4 = 0; j4 < (i + 3) / 4; ++j4) { const f32x4 l = Lr[j4];
;                     if (4 * j4 + 0 < i) a0 -= l[0] * x[4 * j4 + 0];
;                     if (4 * j4 + 1 < i) a1 -= l[1] * x[4 * j4 + 1];
;                     if (4 * j4 + 2 < i) a0 -= l[2] * x[4 * j4 + 2];
;                     if (4 * j4 + 3 < i) a1 -= l[3] * x[4 * j4 + 3]; }
;                 x[i] = a0 + a1; }
	v_fma_f32 v72, -v48, v116, v72
	v_fma_f32 v73, -v49, v117, v73
	v_fma_f32 v74, -v50, v118, v74
	v_fma_f32 v75, -v51, v119, v75
	ds_read_b128 v[48:51], v17 offset:12128
	v_fma_f32 v72, -v52, v120, v72
	v_fma_f32 v73, -v53, v121, v73
	v_fma_f32 v74, -v54, v122, v74
	v_fma_f32 v75, -v55, v123, v75
	ds_read_b128 v[52:55], v17 offset:12144
	s_waitcnt lgkmcnt(10)
	v_fma_f32 v72, -v56, v124, v72
	v_fma_f32 v73, -v57, v125, v73
	v_fma_f32 v74, -v58, v126, v74
	v_fma_f32 v75, -v59, v127, v75
	ds_read_b128 v[56:59], v17 offset:12160
	v_fma_f32 v72, -v4, v128, v72
	v_fma_f32 v73, -v5, v129, v73
	v_fma_f32 v74, -v6, v130, v74
	v_fma_f32 v75, -v7, v131, v75
	ds_read_b128 v[4:7], v17 offset:12176
	s_waitcnt lgkmcnt(10)
	v_fma_f32 v72, -v8, v132, v72
	v_fma_f32 v73, -v9, v133, v73
	v_fma_f32 v74, -v10, v134, v74
	v_fma_f32 v75, -v11, v135, v75
	ds_read_b128 v[8:11], v17 offset:12192
	v_fma_f32 v72, -v12, v136, v72
	v_fma_f32 v73, -v13, v137, v73
	ds_read_b128 v[12:15], v17 offset:12208
	v_add_f32_e32 v72, v72, v73
	v_add_f32_e32 v74, v74, v75
	v_add_f32_e32 v138, v138, v72
	v_add_f32_e32 v138, v138, v74
	s_waitcnt lgkmcnt(10)
	v_mul_f32_e64 v72, -v24, v92
	v_mul_f32_e64 v73, -v25, v93
	v_mul_f32_e64 v74, -v26, v94
	v_mul_f32_e64 v75, -v27, v95
	ds_read_b128 v[24:27], v17 offset:12288
	v_fma_f32 v72, -v28, v96, v72
	v_fma_f32 v73, -v29, v97, v73
	v_fma_f32 v74, -v30, v98, v74
	v_fma_f32 v75, -v31, v99, v75
	ds_read_b128 v[28:31], v17 offset:12304
	s_waitcnt lgkmcnt(10)
	v_fma_f32 v72, -v32, v100, v72
	v_fma_f32 v73, -v33, v101, v73
	v_fma_f32 v74, -v34, v102, v74
	v_fma_f32 v75, -v35, v103, v75
	ds_read_b128 v[32:35], v17 offset:12320
	v_fma_f32 v72, -v36, v104, v72
	v_fma_f32 v73, -v37, v105, v73
	v_fma_f32 v74, -v38, v106, v74
	v_fma_f32 v75, -v39, v107, v75
	ds_read_b128 v[36:39], v17 offset:12336
	s_waitcnt lgkmcnt(10)
	v_fma_f32 v72, -v40, v108, v72
	v_fma_f32 v73, -v41, v109, v73
	v_fma_f32 v74, -v42, v110, v74
	v_fma_f32 v75, -v43, v111, v75
	ds_read_b128 v[40:43], v17 offset:12352
	v_fma_f32 v72, -v44, v112, v72
	v_fma_f32 v73, -v45, v113, v73
	v_fma_f32 v74, -v46, v114, v74
	v_fma_f32 v75, -v47, v115, v75
	ds_read_b128 v[44:47], v17 offset:12368
	s_waitcnt lgkmcnt(10)
	v_fma_f32 v72, -v48, v116, v72
	v_fma_f32 v73, -v49, v117, v73
	v_fma_f32 v74, -v50, v118, v74
	v_fma_f32 v75, -v51, v119, v75
	ds_read_b128 v[48:51], v17 offset:12384
	v_fma_f32 v72, -v52, v120, v72
	v_fma_f32 v73, -v53, v121, v73
	v_fma_f32 v74, -v54, v122, v74
	v_fma_f32 v75, -v55, v123, v75
	ds_read_b128 v[52:55], v17 offset:12400
	s_waitcnt lgkmcnt(10)
	v_fma_f32 v72, -v56, v124, v72
	v_fma_f32 v73, -v57, v125, v73
	v_fma_f32 v74, -v58, v126, v74
	v_fma_f32 v75, -v59, v127, v75
	ds_read_b128 v[56:59], v17 offset:12416
	v_fma_f32 v72, -v4, v128, v72
	v_fma_f32 v73, -v5, v129, v73
	v_fma_f32 v74, -v6, v130, v74
	v_fma_f32 v75, -v7, v131, v75
	ds_read_b128 v[4:7], v17 offset:12432
	s_waitcnt lgkmcnt(10)
	v_fma_f32 v72, -v8, v132, v72
	v_fma_f32 v73, -v9, v133, v73
	v_fma_f32 v74, -v10, v134, v74
	v_fma_f32 v75, -v11, v135, v75
	ds_read_b128 v[8:11], v17 offset:12448
	v_fma_f32 v72, -v12, v136, v72
	v_fma_f32 v73, -v13, v137, v73
	v_fma_f32 v74, -v14, v138, v74
	ds_read_b128 v[12:15], v17 offset:12464
	v_add_f32_e32 v72, v72, v73
	v_add_f32_e32 v74, v74, v75
	v_add_f32_e32 v139, v139, v72
	v_add_f32_e32 v139, v139, v74
	s_waitcnt lgkmcnt(10)
	v_mul_f32_e64 v72, -v24, v92
	v_mul_f32_e64 v73, -v25, v93
	v_mul_f32_e64 v74, -v26, v94
	v_mul_f32_e64 v75, -v27, v95
	ds_read_b128 v[24:27], v17 offset:12544
	v_fma_f32 v72, -v28, v96, v72
	v_fma_f32 v73, -v29, v97, v73
	v_fma_f32 v74, -v30, v98, v74
	v_fma_f32 v75, -v31, v99, v75
	ds_read_b128 v[28:31], v17 offset:12560
	s_waitcnt lgkmcnt(10)
	v_fma_f32 v72, -v32, v100, v72
	v_fma_f32 v73, -v33, v101, v73
	v_fma_f32 v74, -v34, v102, v74
	v_fma_f32 v75, -v35, v103, v75
	ds_read_b128 v[32:35], v17 offset:12576
	v_fma_f32 v72, -v36, v104, v72
	v_fma_f32 v73, -v37, v105, v73
	v_fma_f32 v74, -v38, v106, v74
	v_fma_f32 v75, -v39, v107, v75
	ds_read_b128 v[36:39], v17 offset:12592
	s_waitcnt lgkmcnt(10)
	v_fma_f32 v72, -v40, v108, v72
	v_fma_f32 v73, -v41, v109, v73
	v_fma_f32 v74, -v42, v110, v74
	v_fma_f32 v75, -v43, v111, v75
	ds_read_b128 v[40:43], v17 offset:12608
	v_fma_f32 v72, -v44, v112, v72
	v_fma_f32 v73, -v45, v113, v73
	v_fma_f32 v74, -v46, v114, v74
	v_fma_f32 v75, -v47, v115, v75
	ds_read_b128 v[44:47], v17 offset:12624
	s_waitcnt lgkmcnt(10)
	v_fma_f32 v72, -v48, v116, v72
	v_fma_f32 v73, -v49, v117, v73
	v_fma_f32 v74, -v50, v118, v74
	v_fma_f32 v75, -v51, v119, v75
	ds_read_b128 v[48:51], v17 offset:12640
	v_fma_f32 v72, -v52, v120, v72
	v_fma_f32 v73, -v53, v121, v73
	v_fma_f32 v74, -v54, v122, v74
	v_fma_f32 v75, -v55, v123, v75
	ds_read_b128 v[52:55], v17 offset:12656
	s_waitcnt lgkmcnt(10)
	v_fma_f32 v72, -v56, v124, v72
	v_fma_f32 v73, -v57, v125, v73
	v_fma_f32 v74, -v58, v126, v74
	v_fma_f32 v75, -v59, v127, v75
	ds_read_b128 v[56:59], v17 offset:12672
	v_fma_f32 v72, -v4, v128, v72
	v_fma_f32 v73, -v5, v129, v73
	v_fma_f32 v74, -v6, v130, v74
	v_fma_f32 v75, -v7, v131, v75
	ds_read_b128 v[4:7], v17 offset:12688
	s_waitcnt lgkmcnt(10)
	v_fma_f32 v72, -v8, v132, v72
	v_fma_f32 v73, -v9, v133, v73
	v_fma_f32 v74, -v10, v134, v74
	v_fma_f32 v75, -v11, v135, v75
	ds_read_b128 v[8:11], v17 offset:12704
	v_fma_f32 v72, -v12, v136, v72
	v_fma_f32 v73, -v13, v137, v73
	v_fma_f32 v74, -v14, v138, v74
	v_fma_f32 v75, -v15, v139, v75
	ds_read_b128 v[12:15], v17 offset:12720
	v_add_f32_e32 v72, v72, v73
	v_add_f32_e32 v74, v74, v75
	v_add_f32_e32 v140, v140, v72
	v_add_f32_e32 v140, v140, v74
	s_waitcnt lgkmcnt(10)
; #define LAS __attribute__((address_space(3)))
; __device__ __forceinline__ void even_prep(const Ctx& c, const Params& p, int e) {
;     ...
;             for (int i = 1; i < 64; ++i) { const LAS f32x4* Lr = (const LAS f32x4*)(Lv + i * 64); float a0 = x[i], a1 = 0.f;
; #pragma unroll
;                 for (int j4 = 0; j4 < (i + 3) / 4; ++j4) { const f32x4 l = Lr[j4];
;                     if (4 * j4 + 0 < i) a0 -= l[0] * x[4 * j4 + 0];
;                     if (4 * j4 + 1 < i) a1 -= l[1] * x[4 * j4 + 1];
;                     if (4 * j4 + 2 < i) a0 -= l[2] * x[4 * j4 + 2];
;                     if (4 * j4 + 3 < i) a1 -= l[3] * x[4 * j4 + 3]; }
;                 x[i] = a0 + a1; }
	v_mul_f32_e64 v72, -v24, v92
	v_mul_f32_e64 v73, -v25, v93
	v_mul_f32_e64 v74, -v26, v94
	v_mul_f32_e64 v75, -v27, v95
	ds_read_b128 v[24:27], v17 offset:12736
	v_fma_f32 v72, -v28, v96, v72
	v_fma_f32 v73, -v29, v97, v73
	v_fma_f32 v74, -v30, v98, v74
	v_fma_f32 v75, -v31, v99, v75
	ds_read_b128 v[28:31], v17 offset:12800
	s_waitcnt lgkmcnt(10)
	v_fma_f32 v72, -v32, v100, v72
	v_fma_f32 v73, -v33, v101, v73
	v_fma_f32 v74, -v34, v102, v74
	v_fma_f32 v75, -v35, v103, v75
	ds_read_b128 v[32:35], v17 offset:12816
	v_fma_f32 v72, -v36, v104, v72
	v_fma_f32 v73, -v37, v105, v73
	v_fma_f32 v74, -v38, v106, v74
	v_fma_f32 v75, -v39, v107, v75
	ds_read_b128 v[36:39], v17 offset:12832
	s_waitcnt lgkmcnt(10)
	v_fma_f32 v72, -v40, v108, v72
	v_fma_f32 v73, -v41, v109, v73
	v_fma_f32 v74, -v42, v110, v74
	v_fma_f32 v75, -v43, v111, v75
	ds_read_b128 v[40:43], v17 offset:12848
	v_fma_f32 v72, -v44, v112, v72
	v_fma_f32 v73, -v45, v113, v73
	v_fma_f32 v74, -v46, v114, v74
	v_fma_f32 v75, -v47, v115, v75
	ds_read_b128 v[44:47], v17 offset:12864
	s_waitcnt lgkmcnt(10)
	v_fma_f32 v72, -v48, v116, v72
	v_fma_f32 v73, -v49, v117, v73
	v_fma_f32 v74, -v50, v118, v74
	v_fma_f32 v75, -v51, v119, v75
	ds_read_b128 v[48:51], v17 offset:12880
	v_fma_f32 v72, -v52, v120, v72
	v_fma_f32 v73, -v53, v121, v73
	v_fma_f32 v74, -v54, v122, v74
	v_fma_f32 v75, -v55, v123, v75
	ds_read_b128 v[52:55], v17 offset:12896
	s_waitcnt lgkmcnt(10)
	v_fma_f32 v72, -v56, v124, v72
	v_fma_f32 v73, -v57, v125, v73
	v_fma_f32 v74, -v58, v126, v74
	v_fma_f32 v75, -v59, v127, v75
	ds_read_b128 v[56:59], v17 offset:12912
	v_fma_f32 v72, -v4, v128, v72
	v_fma_f32 v73, -v5, v129, v73
	v_fma_f32 v74, -v6, v130, v74
	v_fma_f32 v75, -v7, v131, v75
	ds_read_b128 v[4:7], v17 offset:12928
	s_waitcnt lgkmcnt(10)
	v_fma_f32 v72, -v8, v132, v72
	v_fma_f32 v73, -v9, v133, v73
	v_fma_f32 v74, -v10, v134, v74
	v_fma_f32 v75, -v11, v135, v75
	ds_read_b128 v[8:11], v17 offset:12944
	v_fma_f32 v72, -v12, v136, v72
	v_fma_f32 v73, -v13, v137, v73
	v_fma_f32 v74, -v14, v138, v74
	v_fma_f32 v75, -v15, v139, v75
	ds_read_b128 v[12:15], v17 offset:12960
	s_waitcnt lgkmcnt(10)
	v_fma_f32 v72, -v24, v140, v72
	ds_read_b128 v[24:27], v17 offset:12976
	v_add_f32_e32 v72, v72, v73
	v_add_f32_e32 v74, v74, v75
	v_add_f32_e32 v141, v141, v72
	v_add_f32_e32 v141, v141, v74
	v_mul_f32_e64 v72, -v28, v92
	v_mul_f32_e64 v73, -v29, v93
	v_mul_f32_e64 v74, -v30, v94
	v_mul_f32_e64 v75, -v31, v95
	ds_read_b128 v[28:31], v17 offset:12992
	s_waitcnt lgkmcnt(10)
	v_fma_f32 v72, -v32, v96, v72
	v_fma_f32 v73, -v33, v97, v73
	v_fma_f32 v74, -v34, v98, v74
	v_fma_f32 v75, -v35, v99, v75
	ds_read_b128 v[32:35], v17 offset:13056
	v_fma_f32 v72, -v36, v100, v72
	v_fma_f32 v73, -v37, v101, v73
	v_fma_f32 v74, -v38, v102, v74
	v_fma_f32 v75, -v39, v103, v75
	ds_read_b128 v[36:39], v17 offset:13072
	s_waitcnt lgkmcnt(10)
	v_fma_f32 v72, -v40, v104, v72
	v_fma_f32 v73, -v41, v105, v73
	v_fma_f32 v74, -v42, v106, v74
	v_fma_f32 v75, -v43, v107, v75
	ds_read_b128 v[40:43], v17 offset:13088
	v_fma_f32 v72, -v44, v108, v72
	v_fma_f32 v73, -v45, v109, v73
	v_fma_f32 v74, -v46, v110, v74
	v_fma_f32 v75, -v47, v111, v75
	ds_read_b128 v[44:47], v17 offset:13104
	s_waitcnt lgkmcnt(10)
	v_fma_f32 v72, -v48, v112, v72
	v_fma_f32 v73, -v49, v113, v73
	v_fma_f32 v74, -v50, v114, v74
	v_fma_f32 v75, -v51, v115, v75
	ds_read_b128 v[48:51], v17 offset:13120
	v_fma_f32 v72, -v52, v116, v72
	v_fma_f32 v73, -v53, v117, v73
	v_fma_f32 v74, -v54, v118, v74
	v_fma_f32 v75, -v55, v119, v75
	ds_read_b128 v[52:55], v17 offset:13136
	s_waitcnt lgkmcnt(10)
	v_fma_f32 v72, -v56, v120, v72
	v_fma_f32 v73, -v57, v121, v73
	v_fma_f32 v74, -v58, v122, v74
	v_fma_f32 v75, -v59, v123, v75
	ds_read_b128 v[56:59], v17 offset:13152
	v_fma_f32 v72, -v4, v124, v72
	v_fma_f32 v73, -v5, v125, v73
	v_fma_f32 v74, -v6, v126, v74
	v_fma_f32 v75, -v7, v127, v75
	ds_read_b128 v[4:7], v17 offset:13168
	s_waitcnt lgkmcnt(10)
	v_fma_f32 v72, -v8, v128, v72
	v_fma_f32 v73, -v9, v129, v73
	v_fma_f32 v74, -v10, v130, v74
	v_fma_f32 v75, -v11, v131, v75
	ds_read_b128 v[8:11], v17 offset:13184
	v_fma_f32 v72, -v12, v132, v72
	v_fma_f32 v73, -v13, v133, v73
	v_fma_f32 v74, -v14, v134, v74
	v_fma_f32 v75, -v15, v135, v75
	ds_read_b128 v[12:15], v17 offset:13200
	s_waitcnt lgkmcnt(10)
	v_fma_f32 v72, -v24, v136, v72
	v_fma_f32 v73, -v25, v137, v73
	v_fma_f32 v74, -v26, v138, v74
	v_fma_f32 v75, -v27, v139, v75
	ds_read_b128 v[24:27], v17 offset:13216
	v_fma_f32 v72, -v28, v140, v72
	v_fma_f32 v73, -v29, v141, v73
	ds_read_b128 v[28:31], v17 offset:13232
	v_add_f32_e32 v72, v72, v73
	v_add_f32_e32 v74, v74, v75
	v_add_f32_e32 v142, v142, v72
	v_add_f32_e32 v142, v142, v74
	s_waitcnt lgkmcnt(10)
	v_mul_f32_e64 v72, -v32, v92
	v_mul_f32_e64 v73, -v33, v93
	v_mul_f32_e64 v74, -v34, v94
	v_mul_f32_e64 v75, -v35, v95
	ds_read_b128 v[32:35], v17 offset:13248
	v_fma_f32 v72, -v36, v96, v72
	v_fma_f32 v73, -v37, v97, v73
	v_fma_f32 v74, -v38, v98, v74
	v_fma_f32 v75, -v39, v99, v75
	ds_read_b128 v[36:39], v17 offset:13312
	s_waitcnt lgkmcnt(10)
	v_fma_f32 v72, -v40, v100, v72
	v_fma_f32 v73, -v41, v101, v73
	v_fma_f32 v74, -v42, v102, v74
	v_fma_f32 v75, -v43, v103, v75
	ds_read_b128 v[40:43], v17 offset:13328
	v_fma_f32 v72, -v44, v104, v72
	v_fma_f32 v73, -v45, v105, v73
	v_fma_f32 v74, -v46, v106, v74
	v_fma_f32 v75, -v47, v107, v75
	ds_read_b128 v[44:47], v17 offset:13344
	s_waitcnt lgkmcnt(10)
	v_fma_f32 v72, -v48, v108, v72
	v_fma_f32 v73, -v49, v109, v73
	v_fma_f32 v74, -v50, v110, v74
	v_fma_f32 v75, -v51, v111, v75
	ds_read_b128 v[48:51], v17 offset:13360
	v_fma_f32 v72, -v52, v112, v72
	v_fma_f32 v73, -v53, v113, v73
	v_fma_f32 v74, -v54, v114, v74
	v_fma_f32 v75, -v55, v115, v75
	ds_read_b128 v[52:55], v17 offset:13376
	s_waitcnt lgkmcnt(10)
; #define LAS __attribute__((address_space(3)))
; __device__ __forceinline__ void even_prep(const Ctx& c, const Params& p, int e) {
;     ...
;             for (int i = 1; i < 64; ++i) { const LAS f32x4* Lr = (const LAS f32x4*)(Lv + i * 64); float a0 = x[i], a1 = 0.f;
; #pragma unroll
;                 for (int j4 = 0; j4 < (i + 3) / 4; ++j4) { const f32x4 l = Lr[j4];
;                     if (4 * j4 + 0 < i) a0 -= l[0] * x[4 * j4 + 0];
;                     if (4 * j4 + 1 < i) a1 -= l[1] * x[4 * j4 + 1];
;                     if (4 * j4 + 2 < i) a0 -= l[2] * x[4 * j4 + 2];
;                     if (4 * j4 + 3 < i) a1 -= l[3] * x[4 * j4 + 3]; }
;                 x[i] = a0 + a1; }
	v_fma_f32 v72, -v56, v116, v72
	v_fma_f32 v73, -v57, v117, v73
	v_fma_f32 v74, -v58, v118, v74
	v_fma_f32 v75, -v59, v119, v75
	ds_read_b128 v[56:59], v17 offset:13392
	v_fma_f32 v72, -v4, v120, v72
	v_fma_f32 v73, -v5, v121, v73
	v_fma_f32 v74, -v6, v122, v74
	v_fma_f32 v75, -v7, v123, v75
	ds_read_b128 v[4:7], v17 offset:13408
	s_waitcnt lgkmcnt(10)
	v_fma_f32 v72, -v8, v124, v72
	v_fma_f32 v73, -v9, v125, v73
	v_fma_f32 v74, -v10, v126, v74
	v_fma_f32 v75, -v11, v127, v75
	ds_read_b128 v[8:11], v17 offset:13424
	v_fma_f32 v72, -v12, v128, v72
	v_fma_f32 v73, -v13, v129, v73
	v_fma_f32 v74, -v14, v130, v74
	v_fma_f32 v75, -v15, v131, v75
	ds_read_b128 v[12:15], v17 offset:13440
	s_waitcnt lgkmcnt(10)
	v_fma_f32 v72, -v24, v132, v72
	v_fma_f32 v73, -v25, v133, v73
	v_fma_f32 v74, -v26, v134, v74
	v_fma_f32 v75, -v27, v135, v75
	ds_read_b128 v[24:27], v17 offset:13456
	v_fma_f32 v72, -v28, v136, v72
	v_fma_f32 v73, -v29, v137, v73
	v_fma_f32 v74, -v30, v138, v74
	v_fma_f32 v75, -v31, v139, v75
	ds_read_b128 v[28:31], v17 offset:13472
	s_waitcnt lgkmcnt(10)
	v_fma_f32 v72, -v32, v140, v72
	v_fma_f32 v73, -v33, v141, v73
	v_fma_f32 v74, -v34, v142, v74
	ds_read_b128 v[32:35], v17 offset:13488
	v_add_f32_e32 v72, v72, v73
	v_add_f32_e32 v74, v74, v75
	v_add_f32_e32 v143, v143, v72
	v_add_f32_e32 v143, v143, v74
	v_mul_f32_e64 v72, -v36, v92
	v_mul_f32_e64 v73, -v37, v93
	v_mul_f32_e64 v74, -v38, v94
	v_mul_f32_e64 v75, -v39, v95
	ds_read_b128 v[36:39], v17 offset:13504
	s_waitcnt lgkmcnt(10)
	v_fma_f32 v72, -v40, v96, v72
	v_fma_f32 v73, -v41, v97, v73
	v_fma_f32 v74, -v42, v98, v74
	v_fma_f32 v75, -v43, v99, v75
	ds_read_b128 v[40:43], v17 offset:13568
	v_fma_f32 v72, -v44, v100, v72
	v_fma_f32 v73, -v45, v101, v73
	v_fma_f32 v74, -v46, v102, v74
	v_fma_f32 v75, -v47, v103, v75
	ds_read_b128 v[44:47], v17 offset:13584
	s_waitcnt lgkmcnt(10)
	v_fma_f32 v72, -v48, v104, v72
	v_fma_f32 v73, -v49, v105, v73
	v_fma_f32 v74, -v50, v106, v74
	v_fma_f32 v75, -v51, v107, v75
	ds_read_b128 v[48:51], v17 offset:13600
	v_fma_f32 v72, -v52, v108, v72
	v_fma_f32 v73, -v53, v109, v73
	v_fma_f32 v74, -v54, v110, v74
	v_fma_f32 v75, -v55, v111, v75
	ds_read_b128 v[52:55], v17 offset:13616
	s_waitcnt lgkmcnt(10)
	v_fma_f32 v72, -v56, v112, v72
	v_fma_f32 v73, -v57, v113, v73
	v_fma_f32 v74, -v58, v114, v74
	v_fma_f32 v75, -v59, v115, v75
	ds_read_b128 v[56:59], v17 offset:13632
	v_fma_f32 v72, -v4, v116, v72
	v_fma_f32 v73, -v5, v117, v73
	v_fma_f32 v74, -v6, v118, v74
	v_fma_f32 v75, -v7, v119, v75
	ds_read_b128 v[4:7], v17 offset:13648
	s_waitcnt lgkmcnt(10)
	v_fma_f32 v72, -v8, v120, v72
	v_fma_f32 v73, -v9, v121, v73
	v_fma_f32 v74, -v10, v122, v74
	v_fma_f32 v75, -v11, v123, v75
	ds_read_b128 v[8:11], v17 offset:13664
	v_fma_f32 v72, -v12, v124, v72
	v_fma_f32 v73, -v13, v125, v73
	v_fma_f32 v74, -v14, v126, v74
	v_fma_f32 v75, -v15, v127, v75
	ds_read_b128 v[12:15], v17 offset:13680
	s_waitcnt lgkmcnt(10)
	v_fma_f32 v72, -v24, v128, v72
	v_fma_f32 v73, -v25, v129, v73
	v_fma_f32 v74, -v26, v130, v74
	v_fma_f32 v75, -v27, v131, v75
	ds_read_b128 v[24:27], v17 offset:13696
	v_fma_f32 v72, -v28, v132, v72
	v_fma_f32 v73, -v29, v133, v73
	v_fma_f32 v74, -v30, v134, v74
	v_fma_f32 v75, -v31, v135, v75
	ds_read_b128 v[28:31], v17 offset:13712
	s_waitcnt lgkmcnt(10)
	v_fma_f32 v72, -v32, v136, v72
	v_fma_f32 v73, -v33, v137, v73
	v_fma_f32 v74, -v34, v138, v74
	v_fma_f32 v75, -v35, v139, v75
	ds_read_b128 v[32:35], v17 offset:13728
	v_fma_f32 v72, -v36, v140, v72
	v_fma_f32 v73, -v37, v141, v73
	v_fma_f32 v74, -v38, v142, v74
	v_fma_f32 v75, -v39, v143, v75
	ds_read_b128 v[36:39], v17 offset:13744
	v_add_f32_e32 v72, v72, v73
	v_add_f32_e32 v74, v74, v75
	v_add_f32_e32 v60, v60, v72
	v_add_f32_e32 v60, v60, v74
	s_waitcnt lgkmcnt(10)
	v_mul_f32_e64 v72, -v40, v92
	v_mul_f32_e64 v73, -v41, v93
	v_mul_f32_e64 v74, -v42, v94
	v_mul_f32_e64 v75, -v43, v95
	ds_read_b128 v[40:43], v17 offset:13760
	v_fma_f32 v72, -v44, v96, v72
	v_fma_f32 v73, -v45, v97, v73
	v_fma_f32 v74, -v46, v98, v74
	v_fma_f32 v75, -v47, v99, v75
	ds_read_b128 v[44:47], v17 offset:13776
	s_waitcnt lgkmcnt(10)
	v_fma_f32 v72, -v48, v100, v72
	v_fma_f32 v73, -v49, v101, v73
	v_fma_f32 v74, -v50, v102, v74
	v_fma_f32 v75, -v51, v103, v75
	ds_read_b128 v[48:51], v17 offset:13824
	v_fma_f32 v72, -v52, v104, v72
	v_fma_f32 v73, -v53, v105, v73
	v_fma_f32 v74, -v54, v106, v74
	v_fma_f32 v75, -v55, v107, v75
	ds_read_b128 v[52:55], v17 offset:13840
	s_waitcnt lgkmcnt(10)
	v_fma_f32 v72, -v56, v108, v72
	v_fma_f32 v73, -v57, v109, v73
	v_fma_f32 v74, -v58, v110, v74
	v_fma_f32 v75, -v59, v111, v75
	ds_read_b128 v[56:59], v17 offset:13856
	v_fma_f32 v72, -v4, v112, v72
	v_fma_f32 v73, -v5, v113, v73
	v_fma_f32 v74, -v6, v114, v74
	v_fma_f32 v75, -v7, v115, v75
	ds_read_b128 v[4:7], v17 offset:13872
	s_waitcnt lgkmcnt(10)
	v_fma_f32 v72, -v8, v116, v72
	v_fma_f32 v73, -v9, v117, v73
	v_fma_f32 v74, -v10, v118, v74
	v_fma_f32 v75, -v11, v119, v75
	ds_read_b128 v[8:11], v17 offset:13888
	v_fma_f32 v72, -v12, v120, v72
	v_fma_f32 v73, -v13, v121, v73
	v_fma_f32 v74, -v14, v122, v74
	v_fma_f32 v75, -v15, v123, v75
	ds_read_b128 v[12:15], v17 offset:13904
	s_waitcnt lgkmcnt(10)
	v_fma_f32 v72, -v24, v124, v72
	v_fma_f32 v73, -v25, v125, v73
	v_fma_f32 v74, -v26, v126, v74
	v_fma_f32 v75, -v27, v127, v75
	ds_read_b128 v[24:27], v17 offset:13920
	v_fma_f32 v72, -v28, v128, v72
	v_fma_f32 v73, -v29, v129, v73
	v_fma_f32 v74, -v30, v130, v74
	v_fma_f32 v75, -v31, v131, v75
	ds_read_b128 v[28:31], v17 offset:13936
	s_waitcnt lgkmcnt(10)
; #define LAS __attribute__((address_space(3)))
; __device__ __forceinline__ void even_prep(const Ctx& c, const Params& p, int e) {
;     ...
;             for (int i = 1; i < 64; ++i) { const LAS f32x4* Lr = (const LAS f32x4*)(Lv + i * 64); float a0 = x[i], a1 = 0.f;
; #pragma unroll
;                 for (int j4 = 0; j4 < (i + 3) / 4; ++j4) { const f32x4 l = Lr[j4];
;                     if (4 * j4 + 0 < i) a0 -= l[0] * x[4 * j4 + 0];
;                     if (4 * j4 + 1 < i) a1 -= l[1] * x[4 * j4 + 1];
;                     if (4 * j4 + 2 < i) a0 -= l[2] * x[4 * j4 + 2];
;                     if (4 * j4 + 3 < i) a1 -= l[3] * x[4 * j4 + 3]; }
;                 x[i] = a0 + a1; }
	v_fma_f32 v72, -v32, v132, v72
	v_fma_f32 v73, -v33, v133, v73
	v_fma_f32 v74, -v34, v134, v74
	v_fma_f32 v75, -v35, v135, v75
	ds_read_b128 v[32:35], v17 offset:13952
	v_fma_f32 v72, -v36, v136, v72
	v_fma_f32 v73, -v37, v137, v73
	v_fma_f32 v74, -v38, v138, v74
	v_fma_f32 v75, -v39, v139, v75
	ds_read_b128 v[36:39], v17 offset:13968
	s_waitcnt lgkmcnt(10)
	v_fma_f32 v72, -v40, v140, v72
	v_fma_f32 v73, -v41, v141, v73
	v_fma_f32 v74, -v42, v142, v74
	v_fma_f32 v75, -v43, v143, v75
	ds_read_b128 v[40:43], v17 offset:13984
	v_fma_f32 v72, -v44, v60, v72
	ds_read_b128 v[44:47], v17 offset:14000
	v_add_f32_e32 v72, v72, v73
	v_add_f32_e32 v74, v74, v75
	v_add_f32_e32 v61, v61, v72
	v_add_f32_e32 v61, v61, v74
	s_waitcnt lgkmcnt(10)
	v_mul_f32_e64 v72, -v48, v92
	v_mul_f32_e64 v73, -v49, v93
	v_mul_f32_e64 v74, -v50, v94
	v_mul_f32_e64 v75, -v51, v95
	ds_read_b128 v[48:51], v17 offset:14016
	v_fma_f32 v72, -v52, v96, v72
	v_fma_f32 v73, -v53, v97, v73
	v_fma_f32 v74, -v54, v98, v74
	v_fma_f32 v75, -v55, v99, v75
	ds_read_b128 v[52:55], v17 offset:14032
	s_waitcnt lgkmcnt(10)
	v_fma_f32 v72, -v56, v100, v72
	v_fma_f32 v73, -v57, v101, v73
	v_fma_f32 v74, -v58, v102, v74
	v_fma_f32 v75, -v59, v103, v75
	ds_read_b128 v[56:59], v17 offset:14080
	v_fma_f32 v72, -v4, v104, v72
	v_fma_f32 v73, -v5, v105, v73
	v_fma_f32 v74, -v6, v106, v74
	v_fma_f32 v75, -v7, v107, v75
	ds_read_b128 v[4:7], v17 offset:14096
	s_waitcnt lgkmcnt(10)
	v_fma_f32 v72, -v8, v108, v72
	v_fma_f32 v73, -v9, v109, v73
	v_fma_f32 v74, -v10, v110, v74
	v_fma_f32 v75, -v11, v111, v75
	ds_read_b128 v[8:11], v17 offset:14112
	v_fma_f32 v72, -v12, v112, v72
	v_fma_f32 v73, -v13, v113, v73
	v_fma_f32 v74, -v14, v114, v74
	v_fma_f32 v75, -v15, v115, v75
	ds_read_b128 v[12:15], v17 offset:14128
	s_waitcnt lgkmcnt(10)
	v_fma_f32 v72, -v24, v116, v72
	v_fma_f32 v73, -v25, v117, v73
	v_fma_f32 v74, -v26, v118, v74
	v_fma_f32 v75, -v27, v119, v75
	ds_read_b128 v[24:27], v17 offset:14144
	v_fma_f32 v72, -v28, v120, v72
	v_fma_f32 v73, -v29, v121, v73
	v_fma_f32 v74, -v30, v122, v74
	v_fma_f32 v75, -v31, v123, v75
	ds_read_b128 v[28:31], v17 offset:14160
	s_waitcnt lgkmcnt(10)
	v_fma_f32 v72, -v32, v124, v72
	v_fma_f32 v73, -v33, v125, v73
	v_fma_f32 v74, -v34, v126, v74
	v_fma_f32 v75, -v35, v127, v75
	ds_read_b128 v[32:35], v17 offset:14176
	v_fma_f32 v72, -v36, v128, v72
	v_fma_f32 v73, -v37, v129, v73
	v_fma_f32 v74, -v38, v130, v74
	v_fma_f32 v75, -v39, v131, v75
	ds_read_b128 v[36:39], v17 offset:14192
	s_waitcnt lgkmcnt(10)
	v_fma_f32 v72, -v40, v132, v72
	v_fma_f32 v73, -v41, v133, v73
	v_fma_f32 v74, -v42, v134, v74
	v_fma_f32 v75, -v43, v135, v75
	ds_read_b128 v[40:43], v17 offset:14208
	v_fma_f32 v72, -v44, v136, v72
	v_fma_f32 v73, -v45, v137, v73
	v_fma_f32 v74, -v46, v138, v74
	v_fma_f32 v75, -v47, v139, v75
	ds_read_b128 v[44:47], v17 offset:14224
	s_waitcnt lgkmcnt(10)
	v_fma_f32 v72, -v48, v140, v72
	v_fma_f32 v73, -v49, v141, v73
	v_fma_f32 v74, -v50, v142, v74
	v_fma_f32 v75, -v51, v143, v75
	ds_read_b128 v[48:51], v17 offset:14240
	v_fma_f32 v72, -v52, v60, v72
	v_fma_f32 v73, -v53, v61, v73
	ds_read_b128 v[52:55], v17 offset:14256
	v_add_f32_e32 v72, v72, v73
	v_add_f32_e32 v74, v74, v75
	v_add_f32_e32 v62, v62, v72
	v_add_f32_e32 v62, v62, v74
	s_waitcnt lgkmcnt(10)
	v_mul_f32_e64 v72, -v56, v92
	v_mul_f32_e64 v73, -v57, v93
	v_mul_f32_e64 v74, -v58, v94
	v_mul_f32_e64 v75, -v59, v95
	ds_read_b128 v[56:59], v17 offset:14272
	v_fma_f32 v72, -v4, v96, v72
	v_fma_f32 v73, -v5, v97, v73
	v_fma_f32 v74, -v6, v98, v74
	v_fma_f32 v75, -v7, v99, v75
	ds_read_b128 v[4:7], v17 offset:14288
	s_waitcnt lgkmcnt(10)
	v_fma_f32 v72, -v8, v100, v72
	v_fma_f32 v73, -v9, v101, v73
	v_fma_f32 v74, -v10, v102, v74
	v_fma_f32 v75, -v11, v103, v75
	ds_read_b128 v[8:11], v17 offset:14336
	v_fma_f32 v72, -v12, v104, v72
	v_fma_f32 v73, -v13, v105, v73
	v_fma_f32 v74, -v14, v106, v74
	v_fma_f32 v75, -v15, v107, v75
	ds_read_b128 v[12:15], v17 offset:14352
	s_waitcnt lgkmcnt(10)
	v_fma_f32 v72, -v24, v108, v72
	v_fma_f32 v73, -v25, v109, v73
	v_fma_f32 v74, -v26, v110, v74
	v_fma_f32 v75, -v27, v111, v75
	ds_read_b128 v[24:27], v17 offset:14368
	v_fma_f32 v72, -v28, v112, v72
	v_fma_f32 v73, -v29, v113, v73
	v_fma_f32 v74, -v30, v114, v74
	v_fma_f32 v75, -v31, v115, v75
	ds_read_b128 v[28:31], v17 offset:14384
	s_waitcnt lgkmcnt(10)
	v_fma_f32 v72, -v32, v116, v72
	v_fma_f32 v73, -v33, v117, v73
	v_fma_f32 v74, -v34, v118, v74
	v_fma_f32 v75, -v35, v119, v75
	ds_read_b128 v[32:35], v17 offset:14400
	v_fma_f32 v72, -v36, v120, v72
	v_fma_f32 v73, -v37, v121, v73
	v_fma_f32 v74, -v38, v122, v74
	v_fma_f32 v75, -v39, v123, v75
	ds_read_b128 v[36:39], v17 offset:14416
	s_waitcnt lgkmcnt(10)
	v_fma_f32 v72, -v40, v124, v72
	v_fma_f32 v73, -v41, v125, v73
	v_fma_f32 v74, -v42, v126, v74
	v_fma_f32 v75, -v43, v127, v75
	ds_read_b128 v[40:43], v17 offset:14432
	v_fma_f32 v72, -v44, v128, v72
	v_fma_f32 v73, -v45, v129, v73
	v_fma_f32 v74, -v46, v130, v74
	v_fma_f32 v75, -v47, v131, v75
	ds_read_b128 v[44:47], v17 offset:14448
	s_waitcnt lgkmcnt(10)
	v_fma_f32 v72, -v48, v132, v72
	v_fma_f32 v73, -v49, v133, v73
	v_fma_f32 v74, -v50, v134, v74
	v_fma_f32 v75, -v51, v135, v75
	ds_read_b128 v[48:51], v17 offset:14464
	v_fma_f32 v72, -v52, v136, v72
	v_fma_f32 v73, -v53, v137, v73
	v_fma_f32 v74, -v54, v138, v74
	v_fma_f32 v75, -v55, v139, v75
	ds_read_b128 v[52:55], v17 offset:14480
	s_waitcnt lgkmcnt(10)
; #define LAS __attribute__((address_space(3)))
; __device__ __forceinline__ void even_prep(const Ctx& c, const Params& p, int e) {
;     ...
;             for (int i = 1; i < 64; ++i) { const LAS f32x4* Lr = (const LAS f32x4*)(Lv + i * 64); float a0 = x[i], a1 = 0.f;
; #pragma unroll
;                 for (int j4 = 0; j4 < (i + 3) / 4; ++j4) { const f32x4 l = Lr[j4];
;                     if (4 * j4 + 0 < i) a0 -= l[0] * x[4 * j4 + 0];
;                     if (4 * j4 + 1 < i) a1 -= l[1] * x[4 * j4 + 1];
;                     if (4 * j4 + 2 < i) a0 -= l[2] * x[4 * j4 + 2];
;                     if (4 * j4 + 3 < i) a1 -= l[3] * x[4 * j4 + 3]; }
;                 x[i] = a0 + a1; }
	v_fma_f32 v72, -v56, v140, v72
	v_fma_f32 v73, -v57, v141, v73
	v_fma_f32 v74, -v58, v142, v74
	v_fma_f32 v75, -v59, v143, v75
	ds_read_b128 v[56:59], v17 offset:14496
	v_fma_f32 v72, -v4, v60, v72
	v_fma_f32 v73, -v5, v61, v73
	v_fma_f32 v74, -v6, v62, v74
	ds_read_b128 v[4:7], v17 offset:14512
	v_add_f32_e32 v72, v72, v73
	v_add_f32_e32 v74, v74, v75
	v_add_f32_e32 v63, v63, v72
	v_add_f32_e32 v63, v63, v74
	s_waitcnt lgkmcnt(10)
	v_mul_f32_e64 v72, -v8, v92
	v_mul_f32_e64 v73, -v9, v93
	v_mul_f32_e64 v74, -v10, v94
	v_mul_f32_e64 v75, -v11, v95
	ds_read_b128 v[8:11], v17 offset:14528
	v_fma_f32 v72, -v12, v96, v72
	v_fma_f32 v73, -v13, v97, v73
	v_fma_f32 v74, -v14, v98, v74
	v_fma_f32 v75, -v15, v99, v75
	ds_read_b128 v[12:15], v17 offset:14544
	s_waitcnt lgkmcnt(10)
	v_fma_f32 v72, -v24, v100, v72
	v_fma_f32 v73, -v25, v101, v73
	v_fma_f32 v74, -v26, v102, v74
	v_fma_f32 v75, -v27, v103, v75
	ds_read_b128 v[24:27], v17 offset:14592
	v_fma_f32 v72, -v28, v104, v72
	v_fma_f32 v73, -v29, v105, v73
	v_fma_f32 v74, -v30, v106, v74
	v_fma_f32 v75, -v31, v107, v75
	ds_read_b128 v[28:31], v17 offset:14608
	s_waitcnt lgkmcnt(10)
	v_fma_f32 v72, -v32, v108, v72
	v_fma_f32 v73, -v33, v109, v73
	v_fma_f32 v74, -v34, v110, v74
	v_fma_f32 v75, -v35, v111, v75
	ds_read_b128 v[32:35], v17 offset:14624
	v_fma_f32 v72, -v36, v112, v72
	v_fma_f32 v73, -v37, v113, v73
	v_fma_f32 v74, -v38, v114, v74
	v_fma_f32 v75, -v39, v115, v75
	ds_read_b128 v[36:39], v17 offset:14640
	s_waitcnt lgkmcnt(10)
	v_fma_f32 v72, -v40, v116, v72
	v_fma_f32 v73, -v41, v117, v73
	v_fma_f32 v74, -v42, v118, v74
	v_fma_f32 v75, -v43, v119, v75
	ds_read_b128 v[40:43], v17 offset:14656
	v_fma_f32 v72, -v44, v120, v72
	v_fma_f32 v73, -v45, v121, v73
	v_fma_f32 v74, -v46, v122, v74
	v_fma_f32 v75, -v47, v123, v75
	ds_read_b128 v[44:47], v17 offset:14672
	s_waitcnt lgkmcnt(10)
	v_fma_f32 v72, -v48, v124, v72
	v_fma_f32 v73, -v49, v125, v73
	v_fma_f32 v74, -v50, v126, v74
	v_fma_f32 v75, -v51, v127, v75
	ds_read_b128 v[48:51], v17 offset:14688
	v_fma_f32 v72, -v52, v128, v72
	v_fma_f32 v73, -v53, v129, v73
	v_fma_f32 v74, -v54, v130, v74
	v_fma_f32 v75, -v55, v131, v75
	ds_read_b128 v[52:55], v17 offset:14704
	s_waitcnt lgkmcnt(10)
	v_fma_f32 v72, -v56, v132, v72
	v_fma_f32 v73, -v57, v133, v73
	v_fma_f32 v74, -v58, v134, v74
	v_fma_f32 v75, -v59, v135, v75
	ds_read_b128 v[56:59], v17 offset:14720
	v_fma_f32 v72, -v4, v136, v72
	v_fma_f32 v73, -v5, v137, v73
	v_fma_f32 v74, -v6, v138, v74
	v_fma_f32 v75, -v7, v139, v75
	ds_read_b128 v[4:7], v17 offset:14736
	s_waitcnt lgkmcnt(10)
	v_fma_f32 v72, -v8, v140, v72
	v_fma_f32 v73, -v9, v141, v73
	v_fma_f32 v74, -v10, v142, v74
	v_fma_f32 v75, -v11, v143, v75
	ds_read_b128 v[8:11], v17 offset:14752
	v_fma_f32 v72, -v12, v60, v72
	v_fma_f32 v73, -v13, v61, v73
	v_fma_f32 v74, -v14, v62, v74
	v_fma_f32 v75, -v15, v63, v75
	ds_read_b128 v[12:15], v17 offset:14768
	v_add_f32_e32 v72, v72, v73
	v_add_f32_e32 v74, v74, v75
	v_add_f32_e32 v64, v64, v72
	v_add_f32_e32 v64, v64, v74
	s_waitcnt lgkmcnt(10)
	v_mul_f32_e64 v72, -v24, v92
	v_mul_f32_e64 v73, -v25, v93
	v_mul_f32_e64 v74, -v26, v94
	v_mul_f32_e64 v75, -v27, v95
	ds_read_b128 v[24:27], v17 offset:14784
	v_fma_f32 v72, -v28, v96, v72
	v_fma_f32 v73, -v29, v97, v73
	v_fma_f32 v74, -v30, v98, v74
	v_fma_f32 v75, -v31, v99, v75
	ds_read_b128 v[28:31], v17 offset:14800
	s_waitcnt lgkmcnt(10)
	v_fma_f32 v72, -v32, v100, v72
	v_fma_f32 v73, -v33, v101, v73
	v_fma_f32 v74, -v34, v102, v74
	v_fma_f32 v75, -v35, v103, v75
	ds_read_b128 v[32:35], v17 offset:14816
	v_fma_f32 v72, -v36, v104, v72
	v_fma_f32 v73, -v37, v105, v73
	v_fma_f32 v74, -v38, v106, v74
	v_fma_f32 v75, -v39, v107, v75
	ds_read_b128 v[36:39], v17 offset:14848
	s_waitcnt lgkmcnt(10)
	v_fma_f32 v72, -v40, v108, v72
	v_fma_f32 v73, -v41, v109, v73
	v_fma_f32 v74, -v42, v110, v74
	v_fma_f32 v75, -v43, v111, v75
	ds_read_b128 v[40:43], v17 offset:14864
	v_fma_f32 v72, -v44, v112, v72
	v_fma_f32 v73, -v45, v113, v73
	v_fma_f32 v74, -v46, v114, v74
	v_fma_f32 v75, -v47, v115, v75
	ds_read_b128 v[44:47], v17 offset:14880
	s_waitcnt lgkmcnt(10)
	v_fma_f32 v72, -v48, v116, v72
	v_fma_f32 v73, -v49, v117, v73
	v_fma_f32 v74, -v50, v118, v74
	v_fma_f32 v75, -v51, v119, v75
	ds_read_b128 v[48:51], v17 offset:14896
	v_fma_f32 v72, -v52, v120, v72
	v_fma_f32 v73, -v53, v121, v73
	v_fma_f32 v74, -v54, v122, v74
	v_fma_f32 v75, -v55, v123, v75
	ds_read_b128 v[52:55], v17 offset:14912
	s_waitcnt lgkmcnt(10)
	v_fma_f32 v72, -v56, v124, v72
	v_fma_f32 v73, -v57, v125, v73
	v_fma_f32 v74, -v58, v126, v74
	v_fma_f32 v75, -v59, v127, v75
	ds_read_b128 v[56:59], v17 offset:14928
	v_fma_f32 v72, -v4, v128, v72
	v_fma_f32 v73, -v5, v129, v73
	v_fma_f32 v74, -v6, v130, v74
	v_fma_f32 v75, -v7, v131, v75
	ds_read_b128 v[4:7], v17 offset:14944
	s_waitcnt lgkmcnt(10)
	v_fma_f32 v72, -v8, v132, v72
	v_fma_f32 v73, -v9, v133, v73
	v_fma_f32 v74, -v10, v134, v74
	v_fma_f32 v75, -v11, v135, v75
	ds_read_b128 v[8:11], v17 offset:14960
	v_fma_f32 v72, -v12, v136, v72
	v_fma_f32 v73, -v13, v137, v73
	v_fma_f32 v74, -v14, v138, v74
	v_fma_f32 v75, -v15, v139, v75
	ds_read_b128 v[12:15], v17 offset:14976
	s_waitcnt lgkmcnt(10)
	v_fma_f32 v72, -v24, v140, v72
	v_fma_f32 v73, -v25, v141, v73
	v_fma_f32 v74, -v26, v142, v74
	v_fma_f32 v75, -v27, v143, v75
	ds_read_b128 v[24:27], v17 offset:14992
	v_fma_f32 v72, -v28, v60, v72
	v_fma_f32 v73, -v29, v61, v73
	v_fma_f32 v74, -v30, v62, v74
	v_fma_f32 v75, -v31, v63, v75
	ds_read_b128 v[28:31], v17 offset:15008
	s_waitcnt lgkmcnt(10)
; #define LAS __attribute__((address_space(3)))
; __device__ __forceinline__ void even_prep(const Ctx& c, const Params& p, int e) {
;     ...
;             for (int i = 1; i < 64; ++i) { const LAS f32x4* Lr = (const LAS f32x4*)(Lv + i * 64); float a0 = x[i], a1 = 0.f;
; #pragma unroll
;                 for (int j4 = 0; j4 < (i + 3) / 4; ++j4) { const f32x4 l = Lr[j4];
;                     if (4 * j4 + 0 < i) a0 -= l[0] * x[4 * j4 + 0];
;                     if (4 * j4 + 1 < i) a1 -= l[1] * x[4 * j4 + 1];
;                     if (4 * j4 + 2 < i) a0 -= l[2] * x[4 * j4 + 2];
;                     if (4 * j4 + 3 < i) a1 -= l[3] * x[4 * j4 + 3]; }
;                 x[i] = a0 + a1; }
	v_fma_f32 v72, -v32, v64, v72
	ds_read_b128 v[32:35], v17 offset:15024
	v_add_f32_e32 v72, v72, v73
	v_add_f32_e32 v74, v74, v75
	v_add_f32_e32 v65, v65, v72
	v_add_f32_e32 v65, v65, v74
	v_mul_f32_e64 v72, -v36, v92
	v_mul_f32_e64 v73, -v37, v93
	v_mul_f32_e64 v74, -v38, v94
	v_mul_f32_e64 v75, -v39, v95
	ds_read_b128 v[36:39], v17 offset:15040
	s_waitcnt lgkmcnt(10)
	v_fma_f32 v72, -v40, v96, v72
	v_fma_f32 v73, -v41, v97, v73
	v_fma_f32 v74, -v42, v98, v74
	v_fma_f32 v75, -v43, v99, v75
	ds_read_b128 v[40:43], v17 offset:15056
	v_fma_f32 v72, -v44, v100, v72
	v_fma_f32 v73, -v45, v101, v73
	v_fma_f32 v74, -v46, v102, v74
	v_fma_f32 v75, -v47, v103, v75
	ds_read_b128 v[44:47], v17 offset:15072
	s_waitcnt lgkmcnt(10)
	v_fma_f32 v72, -v48, v104, v72
	v_fma_f32 v73, -v49, v105, v73
	v_fma_f32 v74, -v50, v106, v74
	v_fma_f32 v75, -v51, v107, v75
	ds_read_b128 v[48:51], v17 offset:15104
	v_fma_f32 v72, -v52, v108, v72
	v_fma_f32 v73, -v53, v109, v73
	v_fma_f32 v74, -v54, v110, v74
	v_fma_f32 v75, -v55, v111, v75
	ds_read_b128 v[52:55], v17 offset:15120
	s_waitcnt lgkmcnt(10)
	v_fma_f32 v72, -v56, v112, v72
	v_fma_f32 v73, -v57, v113, v73
	v_fma_f32 v74, -v58, v114, v74
	v_fma_f32 v75, -v59, v115, v75
	ds_read_b128 v[56:59], v17 offset:15136
	v_fma_f32 v72, -v4, v116, v72
	v_fma_f32 v73, -v5, v117, v73
	v_fma_f32 v74, -v6, v118, v74
	v_fma_f32 v75, -v7, v119, v75
	ds_read_b128 v[4:7], v17 offset:15152
	s_waitcnt lgkmcnt(10)
	v_fma_f32 v72, -v8, v120, v72
	v_fma_f32 v73, -v9, v121, v73
	v_fma_f32 v74, -v10, v122, v74
	v_fma_f32 v75, -v11, v123, v75
	ds_read_b128 v[8:11], v17 offset:15168
	v_fma_f32 v72, -v12, v124, v72
	v_fma_f32 v73, -v13, v125, v73
	v_fma_f32 v74, -v14, v126, v74
	v_fma_f32 v75, -v15, v127, v75
	ds_read_b128 v[12:15], v17 offset:15184
	s_waitcnt lgkmcnt(10)
	v_fma_f32 v72, -v24, v128, v72
	v_fma_f32 v73, -v25, v129, v73
	v_fma_f32 v74, -v26, v130, v74
	v_fma_f32 v75, -v27, v131, v75
	ds_read_b128 v[24:27], v17 offset:15200
	v_fma_f32 v72, -v28, v132, v72
	v_fma_f32 v73, -v29, v133, v73
	v_fma_f32 v74, -v30, v134, v74
	v_fma_f32 v75, -v31, v135, v75
	ds_read_b128 v[28:31], v17 offset:15216
	s_waitcnt lgkmcnt(10)
	v_fma_f32 v72, -v32, v136, v72
	v_fma_f32 v73, -v33, v137, v73
	v_fma_f32 v74, -v34, v138, v74
	v_fma_f32 v75, -v35, v139, v75
	ds_read_b128 v[32:35], v17 offset:15232
	v_fma_f32 v72, -v36, v140, v72
	v_fma_f32 v73, -v37, v141, v73
	v_fma_f32 v74, -v38, v142, v74
	v_fma_f32 v75, -v39, v143, v75
	ds_read_b128 v[36:39], v17 offset:15248
	s_waitcnt lgkmcnt(10)
	v_fma_f32 v72, -v40, v60, v72
	v_fma_f32 v73, -v41, v61, v73
	v_fma_f32 v74, -v42, v62, v74
	v_fma_f32 v75, -v43, v63, v75
	ds_read_b128 v[40:43], v17 offset:15264
	v_fma_f32 v72, -v44, v64, v72
	v_fma_f32 v73, -v45, v65, v73
	ds_read_b128 v[44:47], v17 offset:15280
	v_add_f32_e32 v72, v72, v73
	v_add_f32_e32 v74, v74, v75
	v_add_f32_e32 v66, v66, v72
	v_add_f32_e32 v66, v66, v74
	s_waitcnt lgkmcnt(10)
	v_mul_f32_e64 v72, -v48, v92
	v_mul_f32_e64 v73, -v49, v93
	v_mul_f32_e64 v74, -v50, v94
	v_mul_f32_e64 v75, -v51, v95
	ds_read_b128 v[48:51], v17 offset:15296
	v_fma_f32 v72, -v52, v96, v72
	v_fma_f32 v73, -v53, v97, v73
	v_fma_f32 v74, -v54, v98, v74
	v_fma_f32 v75, -v55, v99, v75
	ds_read_b128 v[52:55], v17 offset:15312
	s_waitcnt lgkmcnt(10)
	v_fma_f32 v72, -v56, v100, v72
	v_fma_f32 v73, -v57, v101, v73
	v_fma_f32 v74, -v58, v102, v74
	v_fma_f32 v75, -v59, v103, v75
	ds_read_b128 v[56:59], v17 offset:15328
	v_fma_f32 v72, -v4, v104, v72
	v_fma_f32 v73, -v5, v105, v73
	v_fma_f32 v74, -v6, v106, v74
	v_fma_f32 v75, -v7, v107, v75
	ds_read_b128 v[4:7], v17 offset:15360
	s_waitcnt lgkmcnt(10)
	v_fma_f32 v72, -v8, v108, v72
	v_fma_f32 v73, -v9, v109, v73
	v_fma_f32 v74, -v10, v110, v74
	v_fma_f32 v75, -v11, v111, v75
	ds_read_b128 v[8:11], v17 offset:15376
	v_fma_f32 v72, -v12, v112, v72
	v_fma_f32 v73, -v13, v113, v73
	v_fma_f32 v74, -v14, v114, v74
	v_fma_f32 v75, -v15, v115, v75
	ds_read_b128 v[12:15], v17 offset:15392
	s_waitcnt lgkmcnt(10)
	v_fma_f32 v72, -v24, v116, v72
	v_fma_f32 v73, -v25, v117, v73
	v_fma_f32 v74, -v26, v118, v74
	v_fma_f32 v75, -v27, v119, v75
	ds_read_b128 v[24:27], v17 offset:15408
	v_fma_f32 v72, -v28, v120, v72
	v_fma_f32 v73, -v29, v121, v73
	v_fma_f32 v74, -v30, v122, v74
	v_fma_f32 v75, -v31, v123, v75
	ds_read_b128 v[28:31], v17 offset:15424
	s_waitcnt lgkmcnt(10)
	v_fma_f32 v72, -v32, v124, v72
	v_fma_f32 v73, -v33, v125, v73
	v_fma_f32 v74, -v34, v126, v74
	v_fma_f32 v75, -v35, v127, v75
	ds_read_b128 v[32:35], v17 offset:15440
	v_fma_f32 v72, -v36, v128, v72
	v_fma_f32 v73, -v37, v129, v73
	v_fma_f32 v74, -v38, v130, v74
	v_fma_f32 v75, -v39, v131, v75
	ds_read_b128 v[36:39], v17 offset:15456
	s_waitcnt lgkmcnt(10)
	v_fma_f32 v72, -v40, v132, v72
	v_fma_f32 v73, -v41, v133, v73
	v_fma_f32 v74, -v42, v134, v74
	v_fma_f32 v75, -v43, v135, v75
	ds_read_b128 v[40:43], v17 offset:15472
	v_fma_f32 v72, -v44, v136, v72
	v_fma_f32 v73, -v45, v137, v73
	v_fma_f32 v74, -v46, v138, v74
	v_fma_f32 v75, -v47, v139, v75
	ds_read_b128 v[44:47], v17 offset:15488
	s_waitcnt lgkmcnt(10)
	v_fma_f32 v72, -v48, v140, v72
	v_fma_f32 v73, -v49, v141, v73
	v_fma_f32 v74, -v50, v142, v74
	v_fma_f32 v75, -v51, v143, v75
	ds_read_b128 v[48:51], v17 offset:15504
	v_fma_f32 v72, -v52, v60, v72
	v_fma_f32 v73, -v53, v61, v73
	v_fma_f32 v74, -v54, v62, v74
	v_fma_f32 v75, -v55, v63, v75
	ds_read_b128 v[52:55], v17 offset:15520
	s_waitcnt lgkmcnt(10)
; #define LAS __attribute__((address_space(3)))
; __device__ __forceinline__ void even_prep(const Ctx& c, const Params& p, int e) {
;     ...
;             for (int i = 1; i < 64; ++i) { const LAS f32x4* Lr = (const LAS f32x4*)(Lv + i * 64); float a0 = x[i], a1 = 0.f;
; #pragma unroll
;                 for (int j4 = 0; j4 < (i + 3) / 4; ++j4) { const f32x4 l = Lr[j4];
;                     if (4 * j4 + 0 < i) a0 -= l[0] * x[4 * j4 + 0];
;                     if (4 * j4 + 1 < i) a1 -= l[1] * x[4 * j4 + 1];
;                     if (4 * j4 + 2 < i) a0 -= l[2] * x[4 * j4 + 2];
;                     if (4 * j4 + 3 < i) a1 -= l[3] * x[4 * j4 + 3]; }
;                 x[i] = a0 + a1; }
	v_fma_f32 v72, -v56, v64, v72
	v_fma_f32 v73, -v57, v65, v73
	v_fma_f32 v74, -v58, v66, v74
	ds_read_b128 v[56:59], v17 offset:15536
	v_add_f32_e32 v72, v72, v73
	v_add_f32_e32 v74, v74, v75
	v_add_f32_e32 v67, v67, v72
	v_add_f32_e32 v67, v67, v74
	v_mul_f32_e64 v72, -v4, v92
	v_mul_f32_e64 v73, -v5, v93
	v_mul_f32_e64 v74, -v6, v94
	v_mul_f32_e64 v75, -v7, v95
	ds_read_b128 v[4:7], v17 offset:15552
	s_waitcnt lgkmcnt(10)
	v_fma_f32 v72, -v8, v96, v72
	v_fma_f32 v73, -v9, v97, v73
	v_fma_f32 v74, -v10, v98, v74
	v_fma_f32 v75, -v11, v99, v75
	ds_read_b128 v[8:11], v17 offset:15568
	v_fma_f32 v72, -v12, v100, v72
	v_fma_f32 v73, -v13, v101, v73
	v_fma_f32 v74, -v14, v102, v74
	v_fma_f32 v75, -v15, v103, v75
	ds_read_b128 v[12:15], v17 offset:15584
	s_waitcnt lgkmcnt(10)
	v_fma_f32 v72, -v24, v104, v72
	v_fma_f32 v73, -v25, v105, v73
	v_fma_f32 v74, -v26, v106, v74
	v_fma_f32 v75, -v27, v107, v75
	ds_read_b128 v[24:27], v17 offset:15616
	v_fma_f32 v72, -v28, v108, v72
	v_fma_f32 v73, -v29, v109, v73
	v_fma_f32 v74, -v30, v110, v74
	v_fma_f32 v75, -v31, v111, v75
	ds_read_b128 v[28:31], v17 offset:15632
	s_waitcnt lgkmcnt(10)
	v_fma_f32 v72, -v32, v112, v72
	v_fma_f32 v73, -v33, v113, v73
	v_fma_f32 v74, -v34, v114, v74
	v_fma_f32 v75, -v35, v115, v75
	ds_read_b128 v[32:35], v17 offset:15648
	v_fma_f32 v72, -v36, v116, v72
	v_fma_f32 v73, -v37, v117, v73
	v_fma_f32 v74, -v38, v118, v74
	v_fma_f32 v75, -v39, v119, v75
	ds_read_b128 v[36:39], v17 offset:15664
	s_waitcnt lgkmcnt(10)
	v_fma_f32 v72, -v40, v120, v72
	v_fma_f32 v73, -v41, v121, v73
	v_fma_f32 v74, -v42, v122, v74
	v_fma_f32 v75, -v43, v123, v75
	ds_read_b128 v[40:43], v17 offset:15680
	v_fma_f32 v72, -v44, v124, v72
	v_fma_f32 v73, -v45, v125, v73
	v_fma_f32 v74, -v46, v126, v74
	v_fma_f32 v75, -v47, v127, v75
	ds_read_b128 v[44:47], v17 offset:15696
	s_waitcnt lgkmcnt(10)
	v_fma_f32 v72, -v48, v128, v72
	v_fma_f32 v73, -v49, v129, v73
	v_fma_f32 v74, -v50, v130, v74
	v_fma_f32 v75, -v51, v131, v75
	ds_read_b128 v[48:51], v17 offset:15712
	v_fma_f32 v72, -v52, v132, v72
	v_fma_f32 v73, -v53, v133, v73
	v_fma_f32 v74, -v54, v134, v74
	v_fma_f32 v75, -v55, v135, v75
	ds_read_b128 v[52:55], v17 offset:15728
	s_waitcnt lgkmcnt(10)
	v_fma_f32 v72, -v56, v136, v72
	v_fma_f32 v73, -v57, v137, v73
	v_fma_f32 v74, -v58, v138, v74
	v_fma_f32 v75, -v59, v139, v75
	ds_read_b128 v[56:59], v17 offset:15744
	v_fma_f32 v72, -v4, v140, v72
	v_fma_f32 v73, -v5, v141, v73
	v_fma_f32 v74, -v6, v142, v74
	v_fma_f32 v75, -v7, v143, v75
	ds_read_b128 v[4:7], v17 offset:15760
	s_waitcnt lgkmcnt(10)
	v_fma_f32 v72, -v8, v60, v72
	v_fma_f32 v73, -v9, v61, v73
	v_fma_f32 v74, -v10, v62, v74
	v_fma_f32 v75, -v11, v63, v75
	ds_read_b128 v[8:11], v17 offset:15776
	v_fma_f32 v72, -v12, v64, v72
	v_fma_f32 v73, -v13, v65, v73
	v_fma_f32 v74, -v14, v66, v74
	v_fma_f32 v75, -v15, v67, v75
	ds_read_b128 v[12:15], v17 offset:15792
	v_add_f32_e32 v72, v72, v73
	v_add_f32_e32 v74, v74, v75
	v_add_f32_e32 v68, v68, v72
	v_add_f32_e32 v68, v68, v74
	s_waitcnt lgkmcnt(10)
	v_mul_f32_e64 v72, -v24, v92
	v_mul_f32_e64 v73, -v25, v93
	v_mul_f32_e64 v74, -v26, v94
	v_mul_f32_e64 v75, -v27, v95
	ds_read_b128 v[24:27], v17 offset:15808
	v_fma_f32 v72, -v28, v96, v72
	v_fma_f32 v73, -v29, v97, v73
	v_fma_f32 v74, -v30, v98, v74
	v_fma_f32 v75, -v31, v99, v75
	ds_read_b128 v[28:31], v17 offset:15824
	s_waitcnt lgkmcnt(10)
	v_fma_f32 v72, -v32, v100, v72
	v_fma_f32 v73, -v33, v101, v73
	v_fma_f32 v74, -v34, v102, v74
	v_fma_f32 v75, -v35, v103, v75
	ds_read_b128 v[32:35], v17 offset:15840
	v_fma_f32 v72, -v36, v104, v72
	v_fma_f32 v73, -v37, v105, v73
	v_fma_f32 v74, -v38, v106, v74
	v_fma_f32 v75, -v39, v107, v75
	ds_read_b128 v[36:39], v17 offset:15856
	s_waitcnt lgkmcnt(10)
	v_fma_f32 v72, -v40, v108, v72
	v_fma_f32 v73, -v41, v109, v73
	v_fma_f32 v74, -v42, v110, v74
	v_fma_f32 v75, -v43, v111, v75
	ds_read_b128 v[40:43], v17 offset:15872
	v_fma_f32 v72, -v44, v112, v72
	v_fma_f32 v73, -v45, v113, v73
	v_fma_f32 v74, -v46, v114, v74
	v_fma_f32 v75, -v47, v115, v75
	ds_read_b128 v[44:47], v17 offset:15888
	s_waitcnt lgkmcnt(10)
	v_fma_f32 v72, -v48, v116, v72
	v_fma_f32 v73, -v49, v117, v73
	v_fma_f32 v74, -v50, v118, v74
	v_fma_f32 v75, -v51, v119, v75
	ds_read_b128 v[48:51], v17 offset:15904
	v_fma_f32 v72, -v52, v120, v72
	v_fma_f32 v73, -v53, v121, v73
	v_fma_f32 v74, -v54, v122, v74
	v_fma_f32 v75, -v55, v123, v75
	ds_read_b128 v[52:55], v17 offset:15920
	s_waitcnt lgkmcnt(10)
	v_fma_f32 v72, -v56, v124, v72
	v_fma_f32 v73, -v57, v125, v73
	v_fma_f32 v74, -v58, v126, v74
	v_fma_f32 v75, -v59, v127, v75
	ds_read_b128 v[56:59], v17 offset:15936
	v_fma_f32 v72, -v4, v128, v72
	v_fma_f32 v73, -v5, v129, v73
	v_fma_f32 v74, -v6, v130, v74
	v_fma_f32 v75, -v7, v131, v75
	ds_read_b128 v[4:7], v17 offset:15952
	s_waitcnt lgkmcnt(10)
	v_fma_f32 v72, -v8, v132, v72
	v_fma_f32 v73, -v9, v133, v73
	v_fma_f32 v74, -v10, v134, v74
	v_fma_f32 v75, -v11, v135, v75
	ds_read_b128 v[8:11], v17 offset:15968
	v_fma_f32 v72, -v12, v136, v72
	v_fma_f32 v73, -v13, v137, v73
	v_fma_f32 v74, -v14, v138, v74
	v_fma_f32 v75, -v15, v139, v75
	ds_read_b128 v[12:15], v17 offset:15984
	s_waitcnt lgkmcnt(10)
	v_fma_f32 v72, -v24, v140, v72
	v_fma_f32 v73, -v25, v141, v73
	v_fma_f32 v74, -v26, v142, v74
	v_fma_f32 v75, -v27, v143, v75
	ds_read_b128 v[24:27], v17 offset:16000
	v_fma_f32 v72, -v28, v60, v72
	v_fma_f32 v73, -v29, v61, v73
	v_fma_f32 v74, -v30, v62, v74
	v_fma_f32 v75, -v31, v63, v75
	ds_read_b128 v[28:31], v17 offset:16016
	s_waitcnt lgkmcnt(10)
; #define LAS __attribute__((address_space(3)))
; __device__ __forceinline__ void even_prep(const Ctx& c, const Params& p, int e) {
;     ...
;             for (int i = 1; i < 64; ++i) { const LAS f32x4* Lr = (const LAS f32x4*)(Lv + i * 64); float a0 = x[i], a1 = 0.f;
; #pragma unroll
;                 for (int j4 = 0; j4 < (i + 3) / 4; ++j4) { const f32x4 l = Lr[j4];
;                     if (4 * j4 + 0 < i) a0 -= l[0] * x[4 * j4 + 0];
;                     if (4 * j4 + 1 < i) a1 -= l[1] * x[4 * j4 + 1];
;                     if (4 * j4 + 2 < i) a0 -= l[2] * x[4 * j4 + 2];
;                     if (4 * j4 + 3 < i) a1 -= l[3] * x[4 * j4 + 3]; }
;                 x[i] = a0 + a1; }
	v_fma_f32 v72, -v32, v64, v72
	v_fma_f32 v73, -v33, v65, v73
	v_fma_f32 v74, -v34, v66, v74
	v_fma_f32 v75, -v35, v67, v75
	ds_read_b128 v[32:35], v17 offset:16032
	v_fma_f32 v72, -v36, v68, v72
	ds_read_b128 v[36:39], v17 offset:16048
	v_add_f32_e32 v72, v72, v73
	v_add_f32_e32 v74, v74, v75
	v_add_f32_e32 v69, v69, v72
	v_add_f32_e32 v69, v69, v74
	s_waitcnt lgkmcnt(10)
	v_mul_f32_e64 v72, -v40, v92
	v_mul_f32_e64 v73, -v41, v93
	v_mul_f32_e64 v74, -v42, v94
	v_mul_f32_e64 v75, -v43, v95
	ds_read_b128 v[40:43], v17 offset:16064
	v_fma_f32 v72, -v44, v96, v72
	v_fma_f32 v73, -v45, v97, v73
	v_fma_f32 v74, -v46, v98, v74
	v_fma_f32 v75, -v47, v99, v75
	ds_read_b128 v[44:47], v17 offset:16080
	s_waitcnt lgkmcnt(10)
	v_fma_f32 v72, -v48, v100, v72
	v_fma_f32 v73, -v49, v101, v73
	v_fma_f32 v74, -v50, v102, v74
	v_fma_f32 v75, -v51, v103, v75
	ds_read_b128 v[48:51], v17 offset:16096
	v_fma_f32 v72, -v52, v104, v72
	v_fma_f32 v73, -v53, v105, v73
	v_fma_f32 v74, -v54, v106, v74
	v_fma_f32 v75, -v55, v107, v75
	ds_read_b128 v[52:55], v17 offset:16112
	s_waitcnt lgkmcnt(10)
	v_fma_f32 v72, -v56, v108, v72
	v_fma_f32 v73, -v57, v109, v73
	v_fma_f32 v74, -v58, v110, v74
	v_fma_f32 v75, -v59, v111, v75
	ds_read_b128 v[56:59], v17 offset:16128
	v_fma_f32 v72, -v4, v112, v72
	v_fma_f32 v73, -v5, v113, v73
	v_fma_f32 v74, -v6, v114, v74
	v_fma_f32 v75, -v7, v115, v75
	ds_read_b128 v[4:7], v17 offset:16144
	s_waitcnt lgkmcnt(10)
	v_fma_f32 v72, -v8, v116, v72
	v_fma_f32 v73, -v9, v117, v73
	v_fma_f32 v74, -v10, v118, v74
	v_fma_f32 v75, -v11, v119, v75
	ds_read_b128 v[8:11], v17 offset:16160
	v_fma_f32 v72, -v12, v120, v72
	v_fma_f32 v73, -v13, v121, v73
	v_fma_f32 v74, -v14, v122, v74
	v_fma_f32 v75, -v15, v123, v75
	ds_read_b128 v[12:15], v17 offset:16176
	s_waitcnt lgkmcnt(10)
	v_fma_f32 v72, -v24, v124, v72
	v_fma_f32 v73, -v25, v125, v73
	v_fma_f32 v74, -v26, v126, v74
	v_fma_f32 v75, -v27, v127, v75
	ds_read_b128 v[24:27], v17 offset:16192
	v_fma_f32 v72, -v28, v128, v72
	v_fma_f32 v73, -v29, v129, v73
	v_fma_f32 v74, -v30, v130, v74
	v_fma_f32 v75, -v31, v131, v75
	ds_read_b128 v[28:31], v17 offset:16208
	s_waitcnt lgkmcnt(10)
	v_fma_f32 v72, -v32, v132, v72
	v_fma_f32 v73, -v33, v133, v73
	v_fma_f32 v74, -v34, v134, v74
	v_fma_f32 v75, -v35, v135, v75
	ds_read_b128 v[32:35], v17 offset:16224
	v_fma_f32 v72, -v36, v136, v72
	v_fma_f32 v73, -v37, v137, v73
	v_fma_f32 v74, -v38, v138, v74
	v_fma_f32 v75, -v39, v139, v75
	ds_read_b128 v[36:39], v17 offset:16240
	s_waitcnt lgkmcnt(10)
	v_fma_f32 v72, -v40, v140, v72
	v_fma_f32 v73, -v41, v141, v73
	v_fma_f32 v74, -v42, v142, v74
	v_fma_f32 v75, -v43, v143, v75
	ds_read_b128 v[40:43], v17 offset:16256
	v_fma_f32 v72, -v44, v60, v72
	v_fma_f32 v73, -v45, v61, v73
	v_fma_f32 v74, -v46, v62, v74
	v_fma_f32 v75, -v47, v63, v75
	ds_read_b128 v[44:47], v17 offset:16272
	s_waitcnt lgkmcnt(10)
	v_fma_f32 v72, -v48, v64, v72
	v_fma_f32 v73, -v49, v65, v73
	v_fma_f32 v74, -v50, v66, v74
	v_fma_f32 v75, -v51, v67, v75
	ds_read_b128 v[48:51], v17 offset:16288
	v_fma_f32 v72, -v52, v68, v72
	v_fma_f32 v73, -v53, v69, v73
	ds_read_b128 v[52:55], v17 offset:16304
	v_add_f32_e32 v72, v72, v73
	v_add_f32_e32 v74, v74, v75
	v_add_f32_e32 v70, v70, v72
	v_add_f32_e32 v70, v70, v74
	s_waitcnt lgkmcnt(10)
	v_mul_f32_e64 v72, -v56, v92
	v_mul_f32_e64 v73, -v57, v93
	v_mul_f32_e64 v74, -v58, v94
	v_mul_f32_e64 v75, -v59, v95
	ds_read_b128 v[56:59], v17 offset:16320
	v_fma_f32 v72, -v4, v96, v72
	v_fma_f32 v73, -v5, v97, v73
	v_fma_f32 v74, -v6, v98, v74
	v_fma_f32 v75, -v7, v99, v75
	ds_read_b128 v[4:7], v17 offset:16336
	s_waitcnt lgkmcnt(10)
	v_fma_f32 v72, -v8, v100, v72
	v_fma_f32 v73, -v9, v101, v73
	v_fma_f32 v74, -v10, v102, v74
	v_fma_f32 v75, -v11, v103, v75
	ds_read_b128 v[8:11], v17 offset:16352
	v_fma_f32 v72, -v12, v104, v72
	v_fma_f32 v73, -v13, v105, v73
	v_fma_f32 v74, -v14, v106, v74
	v_fma_f32 v75, -v15, v107, v75
	ds_read_b128 v[12:15], v17 offset:16368
	s_waitcnt lgkmcnt(10)
	v_fma_f32 v72, -v24, v108, v72
	v_fma_f32 v73, -v25, v109, v73
	v_fma_f32 v74, -v26, v110, v74
	v_fma_f32 v75, -v27, v111, v75
	v_fma_f32 v72, -v28, v112, v72
	v_fma_f32 v73, -v29, v113, v73
	v_fma_f32 v74, -v30, v114, v74
	v_fma_f32 v75, -v31, v115, v75
	s_waitcnt lgkmcnt(8)
	v_fma_f32 v72, -v32, v116, v72
	v_fma_f32 v73, -v33, v117, v73
	v_fma_f32 v74, -v34, v118, v74
	v_fma_f32 v75, -v35, v119, v75
	v_fma_f32 v72, -v36, v120, v72
	v_fma_f32 v73, -v37, v121, v73
	v_fma_f32 v74, -v38, v122, v74
	v_fma_f32 v75, -v39, v123, v75
	s_waitcnt lgkmcnt(6)
	v_fma_f32 v72, -v40, v124, v72
	v_fma_f32 v73, -v41, v125, v73
	v_fma_f32 v74, -v42, v126, v74
	v_fma_f32 v75, -v43, v127, v75
	v_fma_f32 v72, -v44, v128, v72
	v_fma_f32 v73, -v45, v129, v73
	v_fma_f32 v74, -v46, v130, v74
	v_fma_f32 v75, -v47, v131, v75
	s_waitcnt lgkmcnt(4)
	v_fma_f32 v72, -v48, v132, v72
	v_fma_f32 v73, -v49, v133, v73
	v_fma_f32 v74, -v50, v134, v74
	v_fma_f32 v75, -v51, v135, v75
	v_fma_f32 v72, -v52, v136, v72
	v_fma_f32 v73, -v53, v137, v73
	v_fma_f32 v74, -v54, v138, v74
	v_fma_f32 v75, -v55, v139, v75
	s_waitcnt lgkmcnt(2)
; #define LAS __attribute__((address_space(3)))
; __device__ __forceinline__ void even_prep(const Ctx& c, const Params& p, int e) {
;     ...
;             for (int i = 1; i < 64; ++i) { const LAS f32x4* Lr = (const LAS f32x4*)(Lv + i * 64); float a0 = x[i], a1 = 0.f;
; #pragma unroll
;                 for (int j4 = 0; j4 < (i + 3) / 4; ++j4) { const f32x4 l = Lr[j4];
;                     if (4 * j4 + 0 < i) a0 -= l[0] * x[4 * j4 + 0];
;                     if (4 * j4 + 1 < i) a1 -= l[1] * x[4 * j4 + 1];
;                     if (4 * j4 + 2 < i) a0 -= l[2] * x[4 * j4 + 2];
;                     if (4 * j4 + 3 < i) a1 -= l[3] * x[4 * j4 + 3]; }
;                 x[i] = a0 + a1; }
;             LAS float* dstl = (tid_i < 128) ? VB : KBG; const float sg = (tid_i < 128) ? 1.f : -1.f;
; #pragma unroll
;             for (int i = 0; i < 64; ++i) dstl[i * 128 + cc] = x[i] * sg; }
	v_fma_f32 v72, -v56, v140, v72
	v_fma_f32 v73, -v57, v141, v73
	v_fma_f32 v74, -v58, v142, v74
	v_fma_f32 v75, -v59, v143, v75
	v_fma_f32 v72, -v4, v60, v72
	v_fma_f32 v73, -v5, v61, v73
	v_fma_f32 v74, -v6, v62, v74
	v_fma_f32 v75, -v7, v63, v75
	s_waitcnt lgkmcnt(0)
	v_fma_f32 v72, -v8, v64, v72
	v_fma_f32 v73, -v9, v65, v73
	v_fma_f32 v74, -v10, v66, v74
	v_fma_f32 v75, -v11, v67, v75
	v_fma_f32 v72, -v12, v68, v72
	v_fma_f32 v73, -v13, v69, v73
	v_fma_f32 v74, -v14, v70, v74
	v_add_f32_e32 v72, v72, v73
	v_add_f32_e32 v74, v74, v75
	v_add_f32_e32 v71, v71, v72
	v_add_f32_e32 v71, v71, v74
	v_cndmask_b32_e64 v1, -v92, v92, s[4:5]
	v_cndmask_b32_e64 v2, -v93, v93, s[4:5]
	ds_write2st64_b32 v16, v1, v2 offset0:0 offset1:2
	v_cndmask_b32_e64 v1, -v94, v94, s[4:5]
	v_cndmask_b32_e64 v2, -v95, v95, s[4:5]
	ds_write2st64_b32 v16, v1, v2 offset0:4 offset1:6
	v_cndmask_b32_e64 v1, -v96, v96, s[4:5]
	v_cndmask_b32_e64 v2, -v97, v97, s[4:5]
	ds_write2st64_b32 v16, v1, v2 offset0:8 offset1:10
	v_cndmask_b32_e64 v1, -v98, v98, s[4:5]
	v_cndmask_b32_e64 v2, -v99, v99, s[4:5]
	ds_write2st64_b32 v16, v1, v2 offset0:12 offset1:14
	v_cndmask_b32_e64 v1, -v100, v100, s[4:5]
	v_cndmask_b32_e64 v2, -v101, v101, s[4:5]
	ds_write2st64_b32 v16, v1, v2 offset0:16 offset1:18
	v_cndmask_b32_e64 v1, -v102, v102, s[4:5]
	v_cndmask_b32_e64 v2, -v103, v103, s[4:5]
	ds_write2st64_b32 v16, v1, v2 offset0:20 offset1:22
	v_cndmask_b32_e64 v1, -v104, v104, s[4:5]
	v_cndmask_b32_e64 v2, -v105, v105, s[4:5]
	ds_write2st64_b32 v16, v1, v2 offset0:24 offset1:26
	v_cndmask_b32_e64 v1, -v106, v106, s[4:5]
	v_cndmask_b32_e64 v2, -v107, v107, s[4:5]
	ds_write2st64_b32 v16, v1, v2 offset0:28 offset1:30
	v_cndmask_b32_e64 v1, -v108, v108, s[4:5]
	v_cndmask_b32_e64 v2, -v109, v109, s[4:5]
	ds_write2st64_b32 v16, v1, v2 offset0:32 offset1:34
	v_cndmask_b32_e64 v1, -v110, v110, s[4:5]
	v_cndmask_b32_e64 v2, -v111, v111, s[4:5]
	ds_write2st64_b32 v16, v1, v2 offset0:36 offset1:38
	v_cndmask_b32_e64 v1, -v112, v112, s[4:5]
	v_cndmask_b32_e64 v2, -v113, v113, s[4:5]
	ds_write2st64_b32 v16, v1, v2 offset0:40 offset1:42
	v_cndmask_b32_e64 v1, -v114, v114, s[4:5]
	v_cndmask_b32_e64 v2, -v115, v115, s[4:5]
	ds_write2st64_b32 v16, v1, v2 offset0:44 offset1:46
	v_cndmask_b32_e64 v1, -v116, v116, s[4:5]
	v_cndmask_b32_e64 v2, -v117, v117, s[4:5]
	ds_write2st64_b32 v16, v1, v2 offset0:48 offset1:50
	v_cndmask_b32_e64 v1, -v118, v118, s[4:5]
	v_cndmask_b32_e64 v2, -v119, v119, s[4:5]
	ds_write2st64_b32 v16, v1, v2 offset0:52 offset1:54
	v_cndmask_b32_e64 v1, -v120, v120, s[4:5]
	v_cndmask_b32_e64 v2, -v121, v121, s[4:5]
	ds_write2st64_b32 v16, v1, v2 offset0:56 offset1:58
	v_cndmask_b32_e64 v1, -v122, v122, s[4:5]
	v_cndmask_b32_e64 v2, -v123, v123, s[4:5]
	s_waitcnt lgkmcnt(7)
	ds_write2st64_b32 v16, v1, v2 offset0:60 offset1:62
	v_cndmask_b32_e64 v1, -v124, v124, s[4:5]
	v_cndmask_b32_e64 v2, -v125, v125, s[4:5]
	ds_write2st64_b32 v16, v1, v2 offset0:64 offset1:66
	v_cndmask_b32_e64 v1, -v126, v126, s[4:5]
	v_cndmask_b32_e64 v2, -v127, v127, s[4:5]
	ds_write2st64_b32 v16, v1, v2 offset0:68 offset1:70
	v_cndmask_b32_e64 v1, -v128, v128, s[4:5]
	v_cndmask_b32_e64 v2, -v129, v129, s[4:5]
	ds_write2st64_b32 v16, v1, v2 offset0:72 offset1:74
	v_cndmask_b32_e64 v1, -v130, v130, s[4:5]
	v_cndmask_b32_e64 v2, -v131, v131, s[4:5]
	ds_write2st64_b32 v16, v1, v2 offset0:76 offset1:78
	v_cndmask_b32_e64 v1, -v132, v132, s[4:5]
	v_cndmask_b32_e64 v2, -v133, v133, s[4:5]
	ds_write2st64_b32 v16, v1, v2 offset0:80 offset1:82
	v_cndmask_b32_e64 v1, -v134, v134, s[4:5]
	v_cndmask_b32_e64 v2, -v135, v135, s[4:5]
	ds_write2st64_b32 v16, v1, v2 offset0:84 offset1:86
	v_cndmask_b32_e64 v1, -v136, v136, s[4:5]
	v_cndmask_b32_e64 v2, -v137, v137, s[4:5]
	ds_write2st64_b32 v16, v1, v2 offset0:88 offset1:90
	v_cndmask_b32_e64 v1, -v138, v138, s[4:5]
	v_cndmask_b32_e64 v2, -v139, v139, s[4:5]
	s_waitcnt lgkmcnt(7)
	ds_write2st64_b32 v16, v1, v2 offset0:92 offset1:94
	v_cndmask_b32_e64 v1, -v140, v140, s[4:5]
	v_cndmask_b32_e64 v2, -v141, v141, s[4:5]
	ds_write2st64_b32 v16, v1, v2 offset0:96 offset1:98
	v_cndmask_b32_e64 v1, -v142, v142, s[4:5]
	v_cndmask_b32_e64 v2, -v143, v143, s[4:5]
	ds_write2st64_b32 v16, v1, v2 offset0:100 offset1:102
	v_cndmask_b32_e64 v1, -v60, v60, s[4:5]
	v_cndmask_b32_e64 v2, -v61, v61, s[4:5]
	ds_write2st64_b32 v16, v1, v2 offset0:104 offset1:106
	v_cndmask_b32_e64 v1, -v62, v62, s[4:5]
	v_cndmask_b32_e64 v2, -v63, v63, s[4:5]
	ds_write2st64_b32 v16, v1, v2 offset0:108 offset1:110
	v_cndmask_b32_e64 v1, -v64, v64, s[4:5]
	v_cndmask_b32_e64 v2, -v65, v65, s[4:5]
	ds_write2st64_b32 v16, v1, v2 offset0:112 offset1:114
	v_cndmask_b32_e64 v1, -v66, v66, s[4:5]
	v_cndmask_b32_e64 v2, -v67, v67, s[4:5]
	ds_write2st64_b32 v16, v1, v2 offset0:116 offset1:118
	v_cndmask_b32_e64 v1, -v68, v68, s[4:5]
	v_cndmask_b32_e64 v2, -v69, v69, s[4:5]
	ds_write2st64_b32 v16, v1, v2 offset0:120 offset1:122
	v_cndmask_b32_e64 v1, -v70, v70, s[4:5]
	v_cndmask_b32_e64 v2, -v71, v71, s[4:5]
	s_waitcnt lgkmcnt(7)
	ds_write2st64_b32 v16, v1, v2 offset0:124 offset1:126
